# fold + GEMM first-two-waits relaxed past epilogue stores + scan_final prefix chains 4-wide + gates conv loads batched per channel group
# speedup vs baseline: 1.0038x; 1.0038x over previous
; #define LAS __attribute__((address_space(3)))
; #define GAS __attribute__((address_space(1)))
; __global__ void __launch_bounds__(512, 2) fwd_kernel(Args a) {
;     ...
;     const int lo = a.ph_lo, hi_ = a.ph_hi;
;     {
;         volatile LAS unsigned* st0 = (volatile LAS unsigned*)(lds + LDS_MISC);
;         if (threadIdx.x < 2) st0[threadIdx.x] = 0u;
;         __syncthreads();
;         (void)xcd_barrier_post((unsigned*)(a.ws + WS_BAR), st0);
;     }
;     ...
;     cg::grid_group grid = cg::this_grid();
;     ...
;     typedef pg8::EpiBf16<0> EpiB;
;     constexpr int MH = MLAT / 2;
;     ...
;     bool repeated = false;
; #pragma unroll 1
;     for (int ph = lo; ph < hi_; ++ph) {
;         int tid = threadIdx.x; asm volatile("" : "+v"(tid));
;         int G = gridDim.x, bx = blockIdx.x; asm volatile("" : "+s"(G), "+s"(bx));
;         const int lane = tid & 63, wave = __builtin_amdgcn_readfirstlane(tid >> 6);
;         const int vcu = (G % 8 == 0) ? (bx % 8) * (G / 8) + bx / 8 : bx;
;         const int gw = vcu * 8 + wave, NGW = G * 8, gtid = bx * 512 + tid, NTH = G * 512;
;         unsigned char* ws_ = a.ws; asm volatile("" : "+s"(ws_)); GAS unsigned char* ws = (GAS unsigned char*)ws_;
;         GAS float* mod = (GAS float*)(ws + WS_MOD); GAS float* ssq = (GAS float*)(ws + WS_SSQ); GAS float* sskv = (GAS float*)(ws + WS_SSKV);
;         GAS bf16_t* Win = (GAS bf16_t*)(ws + WS_WIN); GAS bf16_t* Wq = (GAS bf16_t*)(ws + WS_WQ); GAS bf16_t* Wkv = (GAS bf16_t*)(ws + WS_WKV); GAS bf16_t* Wg = (GAS bf16_t*)(ws + WS_WG);
;         GAS bf16_t* Wout = (GAS bf16_t*)(ws + WS_WOUT); GAS bf16_t* Wup = (GAS bf16_t*)(ws + WS_WUP); GAS bf16_t* Wdn = (GAS bf16_t*)(ws + WS_WDN);
;         GAS f32x2* AGG = (GAS f32x2*)(ws + WS_AGG); GAS float* RT = (GAS float*)(ws + WS_ROPE);
;         GAS bf16_t* H = (GAS bf16_t*)(ws + WS_R1); GAS bf16_t* KVR = H; GAS bf16_t* H2 = H; GAS bf16_t* QR = (GAS bf16_t*)(ws + WS_Q);
;         GAS bf16_t* P = (GAS bf16_t*)(ws + WS_R2); GAS bf16_t* Y = P; GAS bf16_t* Fb = P;
;         GAS unsigned* LU = (GAS unsigned*)(ws + WS_LU); GAS bf16_t* Kb = (GAS bf16_t*)(ws + WS_K); GAS bf16_t* Vb = (GAS bf16_t*)(ws + WS_V); GAS bf16_t* A2 = (GAS bf16_t*)(ws + WS_A2);
;         GAS bf16_t* UP = (GAS bf16_t*)(ws + WS_UP); GAS bf16_t* Gb = (GAS bf16_t*)(ws + WS_G);
;         float* outp_ = a.out; asm volatile("" : "+s"(outp_)); GAS float* outp = (GAS float*)outp_;
.LBB0_5:
	s_or_b64 exec, exec, s[4:5]
	s_cmp_ge_i32 s44, s45
	s_cbranch_scc1 .LBB0_373
	v_readlane_b32 s2, v253, 4
	v_readlane_b32 s3, v253, 5
	s_load_dword s58, s[2:3], 0xf0
	s_load_dwordx2 s[0:1], s[2:3], 0xf4
	s_add_u32 s2, s2, 0xf0
	s_addc_u32 s3, s3, 0
	v_writelane_b32 v253, s2, 8
	s_cmpk_lt_i32 s33, 0x840
	s_waitcnt lgkmcnt(0)
	s_mul_i32 s0, s0, s58
	v_writelane_b32 v253, s3, 9
	s_mul_i32 s62, s0, s1
	s_cselect_b64 s[0:1], -1, 0
	v_lshrrev_b32_e32 v1, 20, v0
	v_lshrrev_b32_e32 v0, 10, v0
	v_writelane_b32 v253, s0, 10
	v_or_b32_e32 v0, v0, v1
	s_movk_i32 s2, 0x3ff
	v_writelane_b32 v253, s1, 11
	s_add_i32 s0, 0, 0x20040
	v_and_or_b32 v1, v0, s2, v147
	v_writelane_b32 v253, s0, 12
	s_add_i32 s0, 0, 0x20044
	v_mbcnt_lo_u32_b32 v2, -1, 0
	v_writelane_b32 v253, s0, 13
	v_cmp_eq_u32_e64 s[0:1], 0, v1
	s_movk_i32 s68, 0x2000
	s_movk_i32 s63, 0xc0
	s_mov_b32 s69, 0x10000
	v_mov_b32_e32 v0, 0
	s_movk_i32 s70, 0x4000
	s_movk_i32 s46, 0x6000
	s_mov_b32 s47, 0x18000
	s_mov_b32 s49, 0x8000
	s_mov_b32 s59, 0x1e000
	s_mov_b32 s48, 0xc000
	s_movk_i32 s61, 0x7fff
	s_mov_b32 s14, 0x800000
	s_mov_b32 s60, 0x2e8ba2e9
	s_movk_i32 s64, 0x5000
	s_movk_i32 s98, 0x2c00
	s_mov_b32 s99, 0x57fff
	v_mov_b32_e32 v146, 0x358637bd
	s_movk_i32 s15, 0xa000
	s_movk_i32 s50, 0xf8
	s_movk_i32 s92, 0x1ff8
	s_movk_i32 s93, 0x4200
	v_mbcnt_hi_u32_b32 v186, -1, v2
	v_mov_b32_e32 v187, 0x3ecc95a3
	v_mov_b32_e32 v188, 0x3c0881c4
	v_mov_b32_e32 v189, 0xbab64f3b
	v_mov_b32_e32 v190, 1
	v_mov_b32_e32 v191, 0xc00
	v_mov_b32_e32 v192, 0x42000
	v_mov_b32_e32 v193, 0x108000
	v_mov_b32_e32 v194, 0x1c00
	v_mov_b32_e32 v195, 0x1800
	v_mov_b32_e32 v196, 0x400
	v_mov_b32_e32 v197, 0x1400
	v_mov_b32_e32 v198, 0x800
	v_mov_b32_e32 v199, 0x1000
	v_mov_b32_e32 v200, 0xa200a00
	v_mov_b32_e32 v201, 0xa200800
	v_mov_b32_e32 v148, 0x3f317218
	v_mov_b32_e32 v202, 0x7f800000
	v_mov_b32_e32 v203, 0x7fc00000
	v_mov_b32_e32 v204, 0xff800000
	v_not_b32_e32 v205, 63
	v_not_b32_e32 v206, 31
	s_mov_b32 s51, 0
	s_mov_b32 s100, 0
	v_writelane_b32 v253, s0, 14
	s_mov_b64 s[52:53], 0x80
	s_mov_b64 s[54:55], 0x1000
	s_mov_b64 s[66:67], 0xb000
	v_writelane_b32 v253, s1, 15
	s_branch .LBB0_9

; template <class Epi, class Sched, bool ALIGN_EPI = false, bool SP2 = false>
; __device__ __forceinline__ void gemm_phase(PG8_LAS unsigned char* lds, const Gemm g, const Sched& S, const Epi& E, const int tid) {
;     ...
;         if (!has_next) break;
; #pragma unroll
;         for (int a = 0; a < 2; ++a)
; #pragma unroll
;             for (int b = 0; b < 2; ++b)
; #pragma unroll
;                 for (int m = 0; m < 4; ++m)
; #pragma unroll
;                     for (int n = 0; n < 2; ++n) acc[a][b][m][n] = (f32x4){0.f, 0.f, 0.f, 0.f};
;         cur = nxt; cA = nA; cB = nB; ++ui;
.LBB0_57:
	s_mov_b32 s100, 2
	s_mov_b64 s[6:7], 0

; #define PG8_STAGE(bufoff, gbase, voff) do { _Pragma("unroll") for (int _i = 0; _i < 2; ++_i) \
;         __builtin_amdgcn_global_load_lds((const unsigned*)((const char*)(gbase) + (voff)[_i]), (PG8_LAS unsigned*)(lds + (bufoff) + ldsw + _i * 8192), 16, 0, 0); } while (0)
; #define PG8_LDA(dst, b, h) do { _Pragma("unroll") for (int m = 0; m < 4; ++m) _Pragma("unroll") for (int k = 0; k < 2; ++k) dst[m][k] = *(const PG8_LAS bf16x8*)(lds + PG8_SA(b, h) + aoff + m * 2048 + k * 1024); } while (0)
; #define PG8_LDB(dst, b, h) do { _Pragma("unroll") for (int n = 0; n < 2; ++n) _Pragma("unroll") for (int k = 0; k < 2; ++k) dst[n][k] = *(const PG8_LAS bf16x8*)(lds + PG8_SB(b, h) + boff + n * 2048 + k * 1024); } while (0)
; #define PG8_MMA(ai, bj, At, Bt) do { __builtin_amdgcn_s_setprio(1); _Pragma("unroll") for (int m = 0; m < 4; ++m) _Pragma("unroll") for (int n = 0; n < 2; ++n) _Pragma("unroll") for (int k = 0; k < 2; ++k) \
;         acc[ai][bj][m][n] = __builtin_amdgcn_mfma_f32_16x16x32_bf16(Bt[n][k], At[m][k], acc[ai][bj][m][n], 0, 0, 0); __builtin_amdgcn_s_setprio(0); } while (0)
; #define PG8_WAIT_V(n) asm volatile("s_waitcnt vmcnt(" #n ")" ::: "memory")
; #define PG8_WAIT_L(n) asm volatile("s_waitcnt lgkmcnt(" #n ")" ::: "memory")
; #define PG8_BAR __builtin_amdgcn_s_barrier()
; #define PG8_SCHED __builtin_amdgcn_sched_barrier(0)
; template <class Epi, class Sched, bool ALIGN_EPI = false, bool SP2 = false>
; __device__ __forceinline__ void gemm_phase(PG8_LAS unsigned char* lds, const Gemm g, const Sched& S, const Epi& E, const int tid) {
;     ...
;             PG8_LDB(B0, 0, 0); PG8_LDB(B1, 0, 1); PG8_SCHED; PG8_LDA(At, 0, 0); PG8_STAGE(PG8_SA(1, 1), a1 + hstepA, voffA);
;             PG8_WAIT_V(8); PG8_WAIT_L(0); PG8_BAR; PG8_MMA(0, 0, At, B0); PG8_MMA(0, 1, At, B1); PG8_BAR; PG8_SCHED;
;             PG8_LDA(At, 0, 1); PG8_STAGE(PG8_SB(0, 0), b2, voffB); PG8_STAGE(PG8_SB(0, 1), b2 + hstepB, voffB); PG8_STAGE(PG8_SA(0, 0), a2, voffA);
;             PG8_WAIT_V(8); PG8_WAIT_L(0); PG8_BAR; PG8_MMA(1, 0, At, B0); PG8_MMA(1, 1, At, B1); PG8_BAR; PG8_SCHED;
.LBB0_67:
	s_add_i32 s93, s56, 2
	s_add_u32 vcc_lo, s90, 0x80
	s_addc_u32 s57, s91, 0
	s_add_i32 s22, 0, 0x10000
	s_cmp_eq_u32 s70, s56
	s_cselect_b32 s57, s9, s57
	s_cselect_b32 s56, s8, vcc_lo
	v_add_u32_e32 v144, s22, v156
	s_cselect_b32 vcc_hi, s89, s92
	s_cselect_b32 vcc_lo, s88, s25
	s_add_i32 s23, 0, 0x14000
	ds_read_b128 v[150:153], v144
	ds_read_b128 v[160:163], v144 offset:1024
	ds_read_b128 v[164:167], v144 offset:2048
	ds_read_b128 v[168:171], v144 offset:3072
	v_add_u32_e32 v144, s23, v156
	ds_read_b128 v[172:175], v144
	ds_read_b128 v[176:179], v144 offset:1024
	ds_read_b128 v[180:183], v144 offset:2048
	ds_read_b128 v[208:211], v144 offset:3072
	v_lshl_add_u64 v[144:145], s[90:91], 0, v[138:139]
	s_add_i32 m0, s96, 0xc000
	ds_read_b128 v[212:215], v158
	ds_read_b128 v[216:219], v158 offset:1024
	ds_read_b128 v[220:223], v158 offset:2048
	ds_read_b128 v[224:227], v158 offset:3072
	ds_read_b128 v[228:231], v158 offset:4096
	ds_read_b128 v[232:235], v158 offset:5120
	ds_read_b128 v[236:239], v158 offset:6144
	ds_read_b128 v[240:243], v158 offset:7168
	global_load_lds_dwordx4 v[144:145], off
	v_lshl_add_u64 v[144:145], s[90:91], 0, v[140:141]
	s_add_i32 m0, s96, 0xe000
	s_nop 0
	global_load_lds_dwordx4 v[144:145], off
	s_cmp_eq_u32 s100, 0
	s_cbranch_scc1 .Lg_norm1
	s_sub_u32 s100, s100, 1
	s_waitcnt vmcnt(24)
	s_branch .Lg_done1
.Lg_norm1:
	s_waitcnt vmcnt(8)
.Lg_done1:
	s_waitcnt lgkmcnt(0)
	s_barrier
	s_setprio 1
	s_waitcnt lgkmcnt(0)
	v_mfma_f32_16x16x32_bf16 v[126:129], v[150:153], v[212:215], v[126:129]
	v_mfma_f32_16x16x32_bf16 v[122:125], v[164:167], v[212:215], v[122:125]
	v_mfma_f32_16x16x32_bf16 v[118:121], v[150:153], v[220:223], v[118:121]
	v_mfma_f32_16x16x32_bf16 v[114:117], v[164:167], v[220:223], v[114:117]
	v_mfma_f32_16x16x32_bf16 v[106:109], v[150:153], v[228:231], v[106:109]
	v_mfma_f32_16x16x32_bf16 v[98:101], v[164:167], v[228:231], v[98:101]
	v_mfma_f32_16x16x32_bf16 v[90:93], v[150:153], v[236:239], v[90:93]
	v_mfma_f32_16x16x32_bf16 v[82:85], v[164:167], v[236:239], v[82:85]
	v_mfma_f32_16x16x32_bf16 v[126:129], v[160:163], v[216:219], v[126:129]
	v_mfma_f32_16x16x32_bf16 v[122:125], v[168:171], v[216:219], v[122:125]
	v_mfma_f32_16x16x32_bf16 v[118:121], v[160:163], v[224:227], v[118:121]
	v_mfma_f32_16x16x32_bf16 v[114:117], v[168:171], v[224:227], v[114:117]
	v_mfma_f32_16x16x32_bf16 v[106:109], v[160:163], v[232:235], v[106:109]
	v_mfma_f32_16x16x32_bf16 v[98:101], v[168:171], v[232:235], v[98:101]
	v_mfma_f32_16x16x32_bf16 v[90:93], v[160:163], v[240:243], v[90:93]
	v_mfma_f32_16x16x32_bf16 v[82:85], v[168:171], v[240:243], v[82:85]
	s_setprio 0
	s_setprio 1
	v_mfma_f32_16x16x32_bf16 v[110:113], v[172:175], v[212:215], v[110:113]
	v_mfma_f32_16x16x32_bf16 v[102:105], v[180:183], v[212:215], v[102:105]
	v_mfma_f32_16x16x32_bf16 v[94:97], v[172:175], v[220:223], v[94:97]
	v_mfma_f32_16x16x32_bf16 v[86:89], v[180:183], v[220:223], v[86:89]
	v_mfma_f32_16x16x32_bf16 v[78:81], v[172:175], v[228:231], v[78:81]
	v_mfma_f32_16x16x32_bf16 v[74:77], v[180:183], v[228:231], v[74:77]
	v_mfma_f32_16x16x32_bf16 v[70:73], v[172:175], v[236:239], v[70:73]
	v_mfma_f32_16x16x32_bf16 v[66:69], v[180:183], v[236:239], v[66:69]
	v_mfma_f32_16x16x32_bf16 v[110:113], v[176:179], v[216:219], v[110:113]
	v_mfma_f32_16x16x32_bf16 v[102:105], v[208:211], v[216:219], v[102:105]
	v_mfma_f32_16x16x32_bf16 v[94:97], v[176:179], v[224:227], v[94:97]
	v_mfma_f32_16x16x32_bf16 v[86:89], v[208:211], v[224:227], v[86:89]
	v_mfma_f32_16x16x32_bf16 v[78:81], v[176:179], v[232:235], v[78:81]
	v_mfma_f32_16x16x32_bf16 v[74:77], v[208:211], v[232:235], v[74:77]
	v_mfma_f32_16x16x32_bf16 v[70:73], v[176:179], v[240:243], v[70:73]
	v_mfma_f32_16x16x32_bf16 v[66:69], v[208:211], v[240:243], v[66:69]
	s_setprio 0
	s_barrier
	s_add_i32 s22, s22, s43
	v_lshl_add_u64 v[144:145], vcc, 0, v[134:135]
	s_mov_b32 m0, s22
	ds_read_b128 v[212:215], v158 offset:16384
	ds_read_b128 v[216:219], v158 offset:17408
	ds_read_b128 v[220:223], v158 offset:18432
	ds_read_b128 v[224:227], v158 offset:19456
	ds_read_b128 v[228:231], v158 offset:20480
	ds_read_b128 v[232:235], v158 offset:21504
	ds_read_b128 v[236:239], v158 offset:22528
	ds_read_b128 v[240:243], v158 offset:23552
	global_load_lds_dwordx4 v[144:145], off
	s_add_i32 m0, s22, 0x2000
	v_lshl_add_u64 v[154:155], vcc, 0, v[130:131]
	s_add_u32 vcc_lo, vcc_lo, s41
	s_addc_u32 vcc_hi, vcc_hi, 0
	s_add_i32 s22, s23, s43
	global_load_lds_dwordx4 v[154:155], off
	v_lshl_add_u64 v[184:185], vcc, 0, v[134:135]
	s_mov_b32 m0, s22
	v_lshl_add_u64 v[244:245], vcc, 0, v[130:131]
	global_load_lds_dwordx4 v[184:185], off
	s_add_i32 m0, s22, 0x2000
	v_lshl_add_u64 v[246:247], s[56:57], 0, v[136:137]
	global_load_lds_dwordx4 v[244:245], off
	s_mov_b32 m0, s96
	v_lshl_add_u64 v[248:249], s[56:57], 0, v[132:133]
	global_load_lds_dwordx4 v[246:247], off
	s_mov_b32 m0, s97
	s_nop 0
	global_load_lds_dwordx4 v[248:249], off
	s_cmp_eq_u32 s100, 0
	s_cbranch_scc1 .Lg_norm2
	s_sub_u32 s100, s100, 1
	s_waitcnt vmcnt(24)
	s_branch .Lg_done2

; #define PG8_STAGE(bufoff, gbase, voff) do { _Pragma("unroll") for (int _i = 0; _i < 2; ++_i) \
;         __builtin_amdgcn_global_load_lds((const unsigned*)((const char*)(gbase) + (voff)[_i]), (PG8_LAS unsigned*)(lds + (bufoff) + ldsw + _i * 8192), 16, 0, 0); } while (0)
; #define PG8_LDA(dst, b, h) do { _Pragma("unroll") for (int m = 0; m < 4; ++m) _Pragma("unroll") for (int k = 0; k < 2; ++k) dst[m][k] = *(const PG8_LAS bf16x8*)(lds + PG8_SA(b, h) + aoff + m * 2048 + k * 1024); } while (0)
; #define PG8_LDB(dst, b, h) do { _Pragma("unroll") for (int n = 0; n < 2; ++n) _Pragma("unroll") for (int k = 0; k < 2; ++k) dst[n][k] = *(const PG8_LAS bf16x8*)(lds + PG8_SB(b, h) + boff + n * 2048 + k * 1024); } while (0)
; #define PG8_MMA(ai, bj, At, Bt) do { __builtin_amdgcn_s_setprio(1); _Pragma("unroll") for (int m = 0; m < 4; ++m) _Pragma("unroll") for (int n = 0; n < 2; ++n) _Pragma("unroll") for (int k = 0; k < 2; ++k) \
;         acc[ai][bj][m][n] = __builtin_amdgcn_mfma_f32_16x16x32_bf16(Bt[n][k], At[m][k], acc[ai][bj][m][n], 0, 0, 0); __builtin_amdgcn_s_setprio(0); } while (0)
; #define PG8_WAIT_V(n) asm volatile("s_waitcnt vmcnt(" #n ")" ::: "memory")
; #define PG8_WAIT_L(n) asm volatile("s_waitcnt lgkmcnt(" #n ")" ::: "memory")
; #define PG8_BAR __builtin_amdgcn_s_barrier()
; #define PG8_SCHED __builtin_amdgcn_sched_barrier(0)
; template <class Epi, class Sched, bool ALIGN_EPI = false, bool SP2 = false>
; __device__ __forceinline__ void gemm_phase(PG8_LAS unsigned char* lds, const Gemm g, const Sched& S, const Epi& E, const int tid) {
;     ...
;             PG8_WAIT_V(8); PG8_WAIT_L(0); PG8_BAR; PG8_MMA(1, 0, At, B0); PG8_MMA(1, 1, At, B1); PG8_BAR; PG8_SCHED;
;             PG8_LDB(B0, 1, 0); PG8_LDB(B1, 1, 1); PG8_SCHED; PG8_LDA(At, 1, 0); PG8_STAGE(PG8_SA(0, 1), a2 + hstepA, voffA);
;             PG8_WAIT_V(8); PG8_WAIT_L(0); PG8_BAR; PG8_MMA(0, 0, At, B0); PG8_MMA(0, 1, At, B1); PG8_BAR; PG8_SCHED;
.Lg_done2:
	s_waitcnt lgkmcnt(0)
	s_barrier
	s_setprio 1
	s_waitcnt lgkmcnt(0)
	v_mfma_f32_16x16x32_bf16 v[62:65], v[150:153], v[212:215], v[62:65]
	v_mfma_f32_16x16x32_bf16 v[58:61], v[164:167], v[212:215], v[58:61]
	v_mfma_f32_16x16x32_bf16 v[54:57], v[150:153], v[220:223], v[54:57]
	v_mfma_f32_16x16x32_bf16 v[50:53], v[164:167], v[220:223], v[50:53]
	v_mfma_f32_16x16x32_bf16 v[42:45], v[150:153], v[228:231], v[42:45]
	v_mfma_f32_16x16x32_bf16 v[34:37], v[164:167], v[228:231], v[34:37]
	v_mfma_f32_16x16x32_bf16 v[26:29], v[150:153], v[236:239], v[26:29]
	v_mfma_f32_16x16x32_bf16 v[18:21], v[164:167], v[236:239], v[18:21]
	v_mfma_f32_16x16x32_bf16 v[62:65], v[160:163], v[216:219], v[62:65]
	v_mfma_f32_16x16x32_bf16 v[58:61], v[168:171], v[216:219], v[58:61]
	v_mfma_f32_16x16x32_bf16 v[54:57], v[160:163], v[224:227], v[54:57]
	v_mfma_f32_16x16x32_bf16 v[50:53], v[168:171], v[224:227], v[50:53]
	v_mfma_f32_16x16x32_bf16 v[42:45], v[160:163], v[232:235], v[42:45]
	v_mfma_f32_16x16x32_bf16 v[34:37], v[168:171], v[232:235], v[34:37]
	v_mfma_f32_16x16x32_bf16 v[26:29], v[160:163], v[240:243], v[26:29]
	v_mfma_f32_16x16x32_bf16 v[18:21], v[168:171], v[240:243], v[18:21]
	s_setprio 0
	s_setprio 1
	v_mfma_f32_16x16x32_bf16 v[46:49], v[172:175], v[212:215], v[46:49]
	v_mfma_f32_16x16x32_bf16 v[38:41], v[180:183], v[212:215], v[38:41]
	v_mfma_f32_16x16x32_bf16 v[30:33], v[172:175], v[220:223], v[30:33]
	v_mfma_f32_16x16x32_bf16 v[22:25], v[180:183], v[220:223], v[22:25]
	v_mfma_f32_16x16x32_bf16 v[14:17], v[172:175], v[228:231], v[14:17]
	v_mfma_f32_16x16x32_bf16 v[10:13], v[180:183], v[228:231], v[10:13]
	v_mfma_f32_16x16x32_bf16 v[6:9], v[172:175], v[236:239], v[6:9]
	v_mfma_f32_16x16x32_bf16 v[2:5], v[180:183], v[236:239], v[2:5]
	v_mfma_f32_16x16x32_bf16 v[46:49], v[176:179], v[216:219], v[46:49]
	v_mfma_f32_16x16x32_bf16 v[38:41], v[208:211], v[216:219], v[38:41]
	v_mfma_f32_16x16x32_bf16 v[30:33], v[176:179], v[224:227], v[30:33]
	v_mfma_f32_16x16x32_bf16 v[22:25], v[208:211], v[224:227], v[22:25]
	v_mfma_f32_16x16x32_bf16 v[14:17], v[176:179], v[232:235], v[14:17]
	v_mfma_f32_16x16x32_bf16 v[10:13], v[208:211], v[232:235], v[10:13]
	v_mfma_f32_16x16x32_bf16 v[6:9], v[176:179], v[240:243], v[6:9]
	v_mfma_f32_16x16x32_bf16 v[2:5], v[208:211], v[240:243], v[2:5]
	s_setprio 0
	s_barrier
	s_add_i32 s22, 0, 0x18000
	v_add_u32_e32 v159, s22, v156
	s_add_i32 s23, 0, 0x1c000
	ds_read_b128 v[150:153], v159
	ds_read_b128 v[160:163], v159 offset:1024
	ds_read_b128 v[164:167], v159 offset:2048
	ds_read_b128 v[168:171], v159 offset:3072
	v_add_u32_e32 v159, s23, v156
	ds_read_b128 v[172:175], v159
	ds_read_b128 v[176:179], v159 offset:1024
	ds_read_b128 v[180:183], v159 offset:2048
	ds_read_b128 v[208:211], v159 offset:3072
	s_add_u32 s56, s56, s50
	s_addc_u32 s57, s57, 0
	s_mov_b32 m0, s0
	v_lshl_add_u64 v[250:251], s[56:57], 0, v[136:137]
	ds_read_b128 v[212:215], v158 offset:32768
	ds_read_b128 v[216:219], v158 offset:33792
	ds_read_b128 v[220:223], v158 offset:34816
	ds_read_b128 v[224:227], v158 offset:35840
	ds_read_b128 v[228:231], v158 offset:36864
	ds_read_b128 v[232:235], v158 offset:37888
	ds_read_b128 v[236:239], v158 offset:38912
	ds_read_b128 v[240:243], v158 offset:39936
	global_load_lds_dwordx4 v[250:251], off
	v_lshl_add_u64 v[250:251], s[56:57], 0, v[132:133]
	s_mov_b32 m0, s1
	s_nop 0
	global_load_lds_dwordx4 v[250:251], off
	s_waitcnt vmcnt(8)
	s_waitcnt lgkmcnt(0)
	s_barrier
	s_setprio 1
	s_waitcnt lgkmcnt(0)
	v_mfma_f32_16x16x32_bf16 v[126:129], v[150:153], v[212:215], v[126:129]
	v_mfma_f32_16x16x32_bf16 v[122:125], v[164:167], v[212:215], v[122:125]
	v_mfma_f32_16x16x32_bf16 v[118:121], v[150:153], v[220:223], v[118:121]
	v_mfma_f32_16x16x32_bf16 v[114:117], v[164:167], v[220:223], v[114:117]
	v_mfma_f32_16x16x32_bf16 v[106:109], v[150:153], v[228:231], v[106:109]
	v_mfma_f32_16x16x32_bf16 v[98:101], v[164:167], v[228:231], v[98:101]
	v_mfma_f32_16x16x32_bf16 v[90:93], v[150:153], v[236:239], v[90:93]
	v_mfma_f32_16x16x32_bf16 v[82:85], v[164:167], v[236:239], v[82:85]
	v_mfma_f32_16x16x32_bf16 v[126:129], v[160:163], v[216:219], v[126:129]
	v_mfma_f32_16x16x32_bf16 v[122:125], v[168:171], v[216:219], v[122:125]
	v_mfma_f32_16x16x32_bf16 v[118:121], v[160:163], v[224:227], v[118:121]
	v_mfma_f32_16x16x32_bf16 v[114:117], v[168:171], v[224:227], v[114:117]
	v_mfma_f32_16x16x32_bf16 v[106:109], v[160:163], v[232:235], v[106:109]
	v_mfma_f32_16x16x32_bf16 v[98:101], v[168:171], v[232:235], v[98:101]
	v_mfma_f32_16x16x32_bf16 v[90:93], v[160:163], v[240:243], v[90:93]
	v_mfma_f32_16x16x32_bf16 v[82:85], v[168:171], v[240:243], v[82:85]
	s_setprio 0
	s_setprio 1
	v_mfma_f32_16x16x32_bf16 v[110:113], v[172:175], v[212:215], v[110:113]
	v_mfma_f32_16x16x32_bf16 v[102:105], v[180:183], v[212:215], v[102:105]
	v_mfma_f32_16x16x32_bf16 v[94:97], v[172:175], v[220:223], v[94:97]
	v_mfma_f32_16x16x32_bf16 v[86:89], v[180:183], v[220:223], v[86:89]
	v_mfma_f32_16x16x32_bf16 v[78:81], v[172:175], v[228:231], v[78:81]
	v_mfma_f32_16x16x32_bf16 v[74:77], v[180:183], v[228:231], v[74:77]
	v_mfma_f32_16x16x32_bf16 v[70:73], v[172:175], v[236:239], v[70:73]
	v_mfma_f32_16x16x32_bf16 v[66:69], v[180:183], v[236:239], v[66:69]
	v_mfma_f32_16x16x32_bf16 v[110:113], v[176:179], v[216:219], v[110:113]
	v_mfma_f32_16x16x32_bf16 v[102:105], v[208:211], v[216:219], v[102:105]
	v_mfma_f32_16x16x32_bf16 v[94:97], v[176:179], v[224:227], v[94:97]
	v_mfma_f32_16x16x32_bf16 v[86:89], v[208:211], v[224:227], v[86:89]
	v_mfma_f32_16x16x32_bf16 v[78:81], v[176:179], v[232:235], v[78:81]
	v_mfma_f32_16x16x32_bf16 v[74:77], v[208:211], v[232:235], v[74:77]
	v_mfma_f32_16x16x32_bf16 v[70:73], v[176:179], v[240:243], v[70:73]
	v_mfma_f32_16x16x32_bf16 v[66:69], v[208:211], v[240:243], v[66:69]
	s_setprio 0
	s_barrier
; #define PG8_STAGE(bufoff, gbase, voff) do { _Pragma("unroll") for (int _i = 0; _i < 2; ++_i) \
;         __builtin_amdgcn_global_load_lds((const unsigned*)((const char*)(gbase) + (voff)[_i]), (PG8_LAS unsigned*)(lds + (bufoff) + ldsw + _i * 8192), 16, 0, 0); } while (0)
; #define PG8_LDA(dst, b, h) do { _Pragma("unroll") for (int m = 0; m < 4; ++m) _Pragma("unroll") for (int k = 0; k < 2; ++k) dst[m][k] = *(const PG8_LAS bf16x8*)(lds + PG8_SA(b, h) + aoff + m * 2048 + k * 1024); } while (0)
; #define PG8_MMA(ai, bj, At, Bt) do { __builtin_amdgcn_s_setprio(1); _Pragma("unroll") for (int m = 0; m < 4; ++m) _Pragma("unroll") for (int n = 0; n < 2; ++n) _Pragma("unroll") for (int k = 0; k < 2; ++k) \
;         acc[ai][bj][m][n] = __builtin_amdgcn_mfma_f32_16x16x32_bf16(Bt[n][k], At[m][k], acc[ai][bj][m][n], 0, 0, 0); __builtin_amdgcn_s_setprio(0); } while (0)
; #define PG8_WAIT_V(n) asm volatile("s_waitcnt vmcnt(" #n ")" ::: "memory")
; #define PG8_WAIT_L(n) asm volatile("s_waitcnt lgkmcnt(" #n ")" ::: "memory")
; #define PG8_BAR __builtin_amdgcn_s_barrier()
; #define PG8_SCHED __builtin_amdgcn_sched_barrier(0)
;     __device__ __forceinline__ void operator()(const f32x4 (&acc)[2][2][4][2], const Unit& u, int wr, int wc, int fr, int fq) const {
;     ...
;                 for (int bj = 0; bj < 2; ++bj) { f32x4 v0 = acc[ai][bj][m][0] + bv[bj][0], v1 = acc[ai][bj][m][1] + bv[bj][1];
; template <class Epi, class Sched, bool ALIGN_EPI = false, bool SP2 = false>
; __device__ __forceinline__ void gemm_phase(PG8_LAS unsigned char* lds, const Gemm g, const Sched& S, const Epi& E, const int tid) {
;     ...
;             PG8_LDA(At, 1, 1); PG8_STAGE(PG8_SB(1, 0), b3, voffB); PG8_STAGE(PG8_SB(1, 1), b3 + hstepB, voffB); PG8_STAGE(PG8_SA(1, 0), a3, voffA);
;             PG8_WAIT_V(8); PG8_WAIT_L(0); PG8_BAR; PG8_MMA(1, 0, At, B0); PG8_MMA(1, 1, At, B1); PG8_BAR; PG8_SCHED;
	s_add_i32 s22, s22, s43
	v_lshl_add_u64 v[144:145], v[144:145], 0, s[52:53]
	s_mov_b32 m0, s22
	ds_read_b128 v[212:215], v158 offset:49152
	ds_read_b128 v[216:219], v158 offset:50176
	ds_read_b128 v[220:223], v158 offset:51200
	ds_read_b128 v[224:227], v158 offset:52224
	ds_read_b128 v[228:231], v158 offset:53248
	ds_read_b128 v[232:235], v158 offset:54272
	ds_read_b128 v[236:239], v158 offset:55296
	ds_read_b128 v[240:243], v158 offset:56320
	global_load_lds_dwordx4 v[144:145], off
	v_lshl_add_u64 v[144:145], v[154:155], 0, s[52:53]
	s_add_i32 m0, s22, 0x2000
	s_add_i32 s22, s23, s43
	global_load_lds_dwordx4 v[144:145], off
	v_lshl_add_u64 v[144:145], v[184:185], 0, s[52:53]
	s_mov_b32 m0, s22
	s_nop 0
	global_load_lds_dwordx4 v[144:145], off
	v_lshl_add_u64 v[144:145], v[244:245], 0, s[52:53]
	s_add_i32 m0, s22, 0x2000
	s_nop 0
	global_load_lds_dwordx4 v[144:145], off
	v_lshl_add_u64 v[144:145], v[246:247], 0, s[52:53]
	s_mov_b32 m0, s98
	s_nop 0
	global_load_lds_dwordx4 v[144:145], off
	v_lshl_add_u64 v[144:145], v[248:249], 0, s[52:53]
	s_mov_b32 m0, s99
	s_nop 0
	global_load_lds_dwordx4 v[144:145], off
	s_waitcnt vmcnt(8)
	s_waitcnt lgkmcnt(0)
	s_barrier
	s_setprio 1
	s_waitcnt lgkmcnt(0)
	v_mfma_f32_16x16x32_bf16 v[62:65], v[150:153], v[212:215], v[62:65]
	v_mfma_f32_16x16x32_bf16 v[58:61], v[164:167], v[212:215], v[58:61]
	v_mfma_f32_16x16x32_bf16 v[54:57], v[150:153], v[220:223], v[54:57]
	v_mfma_f32_16x16x32_bf16 v[50:53], v[164:167], v[220:223], v[50:53]
	v_mfma_f32_16x16x32_bf16 v[42:45], v[150:153], v[228:231], v[42:45]
	v_mfma_f32_16x16x32_bf16 v[34:37], v[164:167], v[228:231], v[34:37]
	v_mfma_f32_16x16x32_bf16 v[26:29], v[150:153], v[236:239], v[26:29]
	v_mfma_f32_16x16x32_bf16 v[18:21], v[164:167], v[236:239], v[18:21]
	v_mfma_f32_16x16x32_bf16 v[62:65], v[160:163], v[216:219], v[62:65]
	v_mfma_f32_16x16x32_bf16 v[58:61], v[168:171], v[216:219], v[58:61]
	v_mfma_f32_16x16x32_bf16 v[54:57], v[160:163], v[224:227], v[54:57]
	v_mfma_f32_16x16x32_bf16 v[50:53], v[168:171], v[224:227], v[50:53]
	v_mfma_f32_16x16x32_bf16 v[42:45], v[160:163], v[232:235], v[42:45]
	v_mfma_f32_16x16x32_bf16 v[34:37], v[168:171], v[232:235], v[34:37]
	v_mfma_f32_16x16x32_bf16 v[26:29], v[160:163], v[240:243], v[26:29]
	v_mfma_f32_16x16x32_bf16 v[18:21], v[168:171], v[240:243], v[18:21]
	s_setprio 0
	s_setprio 1
	v_mfma_f32_16x16x32_bf16 v[46:49], v[172:175], v[212:215], v[46:49]
	v_mfma_f32_16x16x32_bf16 v[38:41], v[180:183], v[212:215], v[38:41]
	v_mfma_f32_16x16x32_bf16 v[30:33], v[172:175], v[220:223], v[30:33]
	v_mfma_f32_16x16x32_bf16 v[22:25], v[180:183], v[220:223], v[22:25]
	v_mfma_f32_16x16x32_bf16 v[14:17], v[172:175], v[228:231], v[14:17]
	v_mfma_f32_16x16x32_bf16 v[10:13], v[180:183], v[228:231], v[10:13]
	v_mfma_f32_16x16x32_bf16 v[6:9], v[172:175], v[236:239], v[6:9]
	v_mfma_f32_16x16x32_bf16 v[2:5], v[180:183], v[236:239], v[2:5]
	v_mfma_f32_16x16x32_bf16 v[46:49], v[176:179], v[216:219], v[46:49]
	v_mfma_f32_16x16x32_bf16 v[38:41], v[208:211], v[216:219], v[38:41]
	v_mfma_f32_16x16x32_bf16 v[30:33], v[176:179], v[224:227], v[30:33]
	v_mfma_f32_16x16x32_bf16 v[22:25], v[208:211], v[224:227], v[22:25]
	v_mfma_f32_16x16x32_bf16 v[14:17], v[176:179], v[232:235], v[14:17]
	v_mfma_f32_16x16x32_bf16 v[10:13], v[208:211], v[232:235], v[10:13]
	v_mfma_f32_16x16x32_bf16 v[6:9], v[176:179], v[240:243], v[6:9]
	v_mfma_f32_16x16x32_bf16 v[2:5], v[208:211], v[240:243], v[2:5]
	s_setprio 0
	s_barrier
	s_add_u32 s90, s90, 0x100
	s_addc_u32 s91, s91, 0
	s_add_u32 s25, s25, 0x100
	s_addc_u32 s92, s92, 0
	s_cmp_ge_u32 s93, s33
	s_mov_b32 s56, s93
	s_cbranch_scc0 .LBB0_67
	v_pk_add_f32 v[128:129], v[128:129], 0 op_sel_hi:[1,0]
	v_pk_add_f32 v[126:127], v[126:127], 0 op_sel_hi:[1,0]
	v_pk_add_f32 v[124:125], v[124:125], 0 op_sel_hi:[1,0]
	v_pk_add_f32 v[122:123], v[122:123], 0 op_sel_hi:[1,0]
	v_pk_add_f32 v[144:145], v[112:113], 0 op_sel_hi:[1,0]
	v_pk_add_f32 v[150:151], v[110:111], 0 op_sel_hi:[1,0]
	v_pk_add_f32 v[152:153], v[104:105], 0 op_sel_hi:[1,0]
	v_pk_add_f32 v[154:155], v[102:103], 0 op_sel_hi:[1,0]
	v_pk_add_f32 v[102:103], v[120:121], 0 op_sel_hi:[1,0]
	v_pk_add_f32 v[104:105], v[118:119], 0 op_sel_hi:[1,0]
	v_pk_add_f32 v[110:111], v[116:117], 0 op_sel_hi:[1,0]
	v_pk_add_f32 v[112:113], v[114:115], 0 op_sel_hi:[1,0]
	v_pk_add_f32 v[114:115], v[96:97], 0 op_sel_hi:[1,0]
	v_pk_add_f32 v[116:117], v[94:95], 0 op_sel_hi:[1,0]
	v_pk_add_f32 v[118:119], v[88:89], 0 op_sel_hi:[1,0]
	v_pk_add_f32 v[120:121], v[86:87], 0 op_sel_hi:[1,0]
	v_pk_add_f32 v[86:87], v[108:109], 0 op_sel_hi:[1,0]
	v_pk_add_f32 v[88:89], v[106:107], 0 op_sel_hi:[1,0]
	v_pk_add_f32 v[94:95], v[100:101], 0 op_sel_hi:[1,0]
	v_pk_add_f32 v[96:97], v[98:99], 0 op_sel_hi:[1,0]
	v_pk_add_f32 v[98:99], v[80:81], 0 op_sel_hi:[1,0]
	v_pk_add_f32 v[100:101], v[78:79], 0 op_sel_hi:[1,0]
	v_pk_add_f32 v[106:107], v[76:77], 0 op_sel_hi:[1,0]
	v_pk_add_f32 v[108:109], v[74:75], 0 op_sel_hi:[1,0]
	v_pk_add_f32 v[74:75], v[92:93], 0 op_sel_hi:[1,0]
	v_pk_add_f32 v[76:77], v[90:91], 0 op_sel_hi:[1,0]
	v_pk_add_f32 v[78:79], v[84:85], 0 op_sel_hi:[1,0]
	v_pk_add_f32 v[80:81], v[82:83], 0 op_sel_hi:[1,0]
	v_pk_add_f32 v[72:73], v[72:73], 0 op_sel_hi:[1,0]
	v_pk_add_f32 v[70:71], v[70:71], 0 op_sel_hi:[1,0]
	v_pk_add_f32 v[68:69], v[68:69], 0 op_sel_hi:[1,0]
	v_pk_add_f32 v[66:67], v[66:67], 0 op_sel_hi:[1,0]
	v_pk_add_f32 v[64:65], v[64:65], 0 op_sel_hi:[1,0]
	v_pk_add_f32 v[62:63], v[62:63], 0 op_sel_hi:[1,0]
	v_pk_add_f32 v[60:61], v[60:61], 0 op_sel_hi:[1,0]
	v_pk_add_f32 v[58:59], v[58:59], 0 op_sel_hi:[1,0]
	v_pk_add_f32 v[82:83], v[48:49], 0 op_sel_hi:[1,0]
	v_pk_add_f32 v[84:85], v[46:47], 0 op_sel_hi:[1,0]
	v_pk_add_f32 v[90:91], v[40:41], 0 op_sel_hi:[1,0]
	v_pk_add_f32 v[92:93], v[38:39], 0 op_sel_hi:[1,0]
	v_pk_add_f32 v[38:39], v[56:57], 0 op_sel_hi:[1,0]
	v_pk_add_f32 v[40:41], v[54:55], 0 op_sel_hi:[1,0]
	v_pk_add_f32 v[46:47], v[52:53], 0 op_sel_hi:[1,0]
	v_pk_add_f32 v[48:49], v[50:51], 0 op_sel_hi:[1,0]
	v_pk_add_f32 v[50:51], v[32:33], 0 op_sel_hi:[1,0]
	v_pk_add_f32 v[52:53], v[30:31], 0 op_sel_hi:[1,0]
	v_pk_add_f32 v[54:55], v[24:25], 0 op_sel_hi:[1,0]
	v_pk_add_f32 v[56:57], v[22:23], 0 op_sel_hi:[1,0]
	v_pk_add_f32 v[22:23], v[44:45], 0 op_sel_hi:[1,0]
	v_pk_add_f32 v[24:25], v[42:43], 0 op_sel_hi:[1,0]
	v_pk_add_f32 v[30:31], v[36:37], 0 op_sel_hi:[1,0]
	v_pk_add_f32 v[32:33], v[34:35], 0 op_sel_hi:[1,0]
	v_pk_add_f32 v[34:35], v[16:17], 0 op_sel_hi:[1,0]
	v_pk_add_f32 v[36:37], v[14:15], 0 op_sel_hi:[1,0]
	v_pk_add_f32 v[42:43], v[12:13], 0 op_sel_hi:[1,0]
	v_pk_add_f32 v[44:45], v[10:11], 0 op_sel_hi:[1,0]
	v_pk_add_f32 v[10:11], v[28:29], 0 op_sel_hi:[1,0]
	v_pk_add_f32 v[12:13], v[26:27], 0 op_sel_hi:[1,0]
	v_pk_add_f32 v[14:15], v[20:21], 0 op_sel_hi:[1,0]
	v_pk_add_f32 v[16:17], v[18:19], 0 op_sel_hi:[1,0]
	v_pk_add_f32 v[8:9], v[8:9], 0 op_sel_hi:[1,0]
	v_pk_add_f32 v[6:7], v[6:7], 0 op_sel_hi:[1,0]
	v_pk_add_f32 v[4:5], v[4:5], 0 op_sel_hi:[1,0]
	v_pk_add_f32 v[2:3], v[2:3], 0 op_sel_hi:[1,0]

; __device__ __forceinline__ void scan_final(const GAS unsigned* __restrict__ LU, const GAS f32x2* __restrict__ AGG, const GAS bf16_t* __restrict__ P, GAS bf16_t* __restrict__ A2, int gw, int NGW, int lane) {
;     ...
;         for (int cc = 0; cc < c; ++cc) { const f32x2 g = ag0[(size_t)cc * 512]; hf = g.x * hf + g.y; }
.LBB0_117:
	s_cmp_lt_u32 s26, 0x4000
	s_cbranch_scc1 .Lsf_f1
.Lsf_f4:
	v_lshl_add_u64 v[116:117], v[42:43], 0, s[54:55]
	v_lshl_add_u64 v[118:119], v[116:117], 0, s[54:55]
	v_lshl_add_u64 v[120:121], v[118:119], 0, s[54:55]
	global_load_dwordx2 v[48:49], v[42:43], off
	global_load_dwordx2 v[122:123], v[116:117], off
	global_load_dwordx2 v[124:125], v[118:119], off
	global_load_dwordx2 v[126:127], v[120:121], off
	v_lshl_add_u64 v[42:43], v[120:121], 0, s[54:55]
	s_sub_u32 s26, s26, 0x4000
	s_waitcnt vmcnt(0)
	v_fma_f32 v45, v45, v48, v49
	v_fma_f32 v45, v45, v122, v123
	v_fma_f32 v45, v45, v124, v125
	v_fma_f32 v45, v45, v126, v127
	s_cmp_lt_u32 s26, 0x4000
	s_cbranch_scc0 .Lsf_f4
.Lsf_f1:
	s_cmp_eq_u32 s26, 0
	s_cbranch_scc1 .LBB0_118

.LBB0_120:
	s_movk_i32 s26, 0xf000
	s_mov_b32 s27, -1
	s_sub_i32 s13, s12, s25
	s_cmp_lt_u32 s13, 4
	s_cbranch_scc1 .Lsf_b1
.Lsf_b4:
	v_lshl_add_u64 v[116:117], v[38:39], 0, s[26:27]
	v_lshl_add_u64 v[118:119], v[116:117], 0, s[26:27]
	v_lshl_add_u64 v[120:121], v[118:119], 0, s[26:27]
	global_load_dwordx2 v[42:43], v[38:39], off
	global_load_dwordx2 v[122:123], v[116:117], off
	global_load_dwordx2 v[124:125], v[118:119], off
	global_load_dwordx2 v[126:127], v[120:121], off
	v_lshl_add_u64 v[38:39], v[120:121], 0, s[26:27]
	s_add_i32 s12, s12, -4
	s_add_i32 s13, s13, -4
	s_waitcnt vmcnt(0)
	v_fma_f32 v41, v41, v42, v43
	v_fma_f32 v41, v41, v122, v123
	v_fma_f32 v41, v41, v124, v125
	v_fma_f32 v41, v41, v126, v127
	s_cmp_lt_u32 s13, 4
	s_cbranch_scc0 .Lsf_b4
.Lsf_b1:
	s_cmp_eq_u32 s13, 0
	s_cbranch_scc1 .LBB0_121

; #define GAS __attribute__((address_space(1)))
; __global__ void __launch_bounds__(512, 2) fwd_kernel(Args a) {
;     ...
;     for (int ph = lo; ph < hi_; ++ph) {
;         int tid = threadIdx.x; asm volatile("" : "+v"(tid));
;         int G = gridDim.x, bx = blockIdx.x; asm volatile("" : "+s"(G), "+s"(bx));
;         const int lane = tid & 63, wave = __builtin_amdgcn_readfirstlane(tid >> 6);
;         const int vcu = (G % 8 == 0) ? (bx % 8) * (G / 8) + bx / 8 : bx;
;         const int gw = vcu * 8 + wave, NGW = G * 8, gtid = bx * 512 + tid, NTH = G * 512;
;         unsigned char* ws_ = a.ws; asm volatile("" : "+s"(ws_)); GAS unsigned char* ws = (GAS unsigned char*)ws_;
;         GAS float* mod = (GAS float*)(ws + WS_MOD); GAS float* ssq = (GAS float*)(ws + WS_SSQ); GAS float* sskv = (GAS float*)(ws + WS_SSKV);
;         GAS bf16_t* Win = (GAS bf16_t*)(ws + WS_WIN); GAS bf16_t* Wq = (GAS bf16_t*)(ws + WS_WQ); GAS bf16_t* Wkv = (GAS bf16_t*)(ws + WS_WKV); GAS bf16_t* Wg = (GAS bf16_t*)(ws + WS_WG);
;         GAS bf16_t* Wout = (GAS bf16_t*)(ws + WS_WOUT); GAS bf16_t* Wup = (GAS bf16_t*)(ws + WS_WUP); GAS bf16_t* Wdn = (GAS bf16_t*)(ws + WS_WDN);
;         GAS f32x2* AGG = (GAS f32x2*)(ws + WS_AGG); GAS float* RT = (GAS float*)(ws + WS_ROPE);
;         GAS bf16_t* H = (GAS bf16_t*)(ws + WS_R1); GAS bf16_t* KVR = H; GAS bf16_t* H2 = H; GAS bf16_t* QR = (GAS bf16_t*)(ws + WS_Q);
;         GAS bf16_t* P = (GAS bf16_t*)(ws + WS_R2); GAS bf16_t* Y = P; GAS bf16_t* Fb = P;
;         GAS unsigned* LU = (GAS unsigned*)(ws + WS_LU); GAS bf16_t* Kb = (GAS bf16_t*)(ws + WS_K); GAS bf16_t* Vb = (GAS bf16_t*)(ws + WS_V); GAS bf16_t* A2 = (GAS bf16_t*)(ws + WS_A2);
;         GAS bf16_t* UP = (GAS bf16_t*)(ws + WS_UP); GAS bf16_t* Gb = (GAS bf16_t*)(ws + WS_G);
;         float* outp_ = a.out; asm volatile("" : "+s"(outp_)); GAS float* outp = (GAS float*)outp_;
.LBB0_149:
	s_mov_b32 s100, 0
	v_mov_b32_e32 v188, 0x3c0881c4
	v_mov_b32_e32 v189, 0xbab64f3b
	v_mov_b32_e32 v190, 1
	v_mov_b32_e32 v191, 0xc00
	v_mov_b32_e32 v192, 0x42000
	v_mov_b32_e32 v193, 0x108000
	v_mov_b32_e32 v194, 0x1c00
	v_mov_b32_e32 v195, 0x1800
	v_mov_b32_e32 v196, 0x400
	v_mov_b32_e32 v197, 0x1400
	v_mov_b32_e32 v198, 0x800
	v_mov_b32_e32 v199, 0x1000
	v_mov_b32_e32 v200, 0xa200a00
	v_mov_b32_e32 v201, 0xa200800
	v_mov_b32_e32 v202, 0x7f800000
	v_mov_b32_e32 v203, 0x7fc00000
	s_mov_b32 s49, 0x8000
	s_mov_b32 s60, 0x2e8ba2e9
	s_movk_i32 s64, 0x5000
	s_movk_i32 s98, 0x2c00
	s_mov_b32 s99, 0x57fff
	s_movk_i32 s50, 0xf8
	s_movk_i32 s92, 0x1ff8
	s_movk_i32 s93, 0x4200

; #define LAS __attribute__((address_space(3)))
; #define GAS __attribute__((address_space(1)))
; __device__ __forceinline__ unsigned pk2(float lo, float hi) { return cvtpk(lo, hi); }
; __device__ __forceinline__ float bflo(unsigned w) { return __uint_as_float(w << 16); }
; __device__ __forceinline__ float bfhi(unsigned w) { return __uint_as_float(w & 0xffff0000u); }
; __device__ __forceinline__ void gates_phase(const GAS float* __restrict__ cw, const GAS float* __restrict__ cb, const GAS float* __restrict__ b_a, const GAS float* __restrict__ b_x, const GAS float* __restrict__ lam, LAS unsigned char* lds, const GAS bf16_t* __restrict__ P, const GAS bf16_t* __restr ...
;     ...
;             for (int c8 = 0; c8 < 4; ++c8) { const int ch = (lane & 1) * 32 + c8 * 8, gch = h * 64 + ch;
;                 float acc[8];
;                 { const f32x4 b0 = *(const GAS f32x4*)(cb + gch), b1 = *(const GAS f32x4*)(cb + gch + 4);
;                   acc[0] = b0.x; acc[1] = b0.y; acc[2] = b0.z; acc[3] = b0.w; acc[4] = b1.x; acc[5] = b1.y; acc[6] = b1.z; acc[7] = b1.w; }
; #pragma unroll
;                 for (int k = 0; k < 4; ++k) { const int mm = m + k - 2;
;                     if (mm >= s0 && mm < s0 + slen) { const u32x4 xv = *(const GAS u32x4*)(P + (size_t)mm * PW + gch);
;                         const f32x4 w0 = *(const GAS f32x4*)(cw + k * 512 + gch), w1 = *(const GAS f32x4*)(cw + k * 512 + gch + 4);
;                         acc[0] += w0.x * bflo(xv.x); acc[1] += w0.y * bfhi(xv.x); acc[2] += w0.z * bflo(xv.y); acc[3] += w0.w * bfhi(xv.y);
;                         acc[4] += w1.x * bflo(xv.z); acc[5] += w1.y * bfhi(xv.z); acc[6] += w1.z * bflo(xv.w); acc[7] += w1.w * bfhi(xv.w); } }
;                 u32x4 o; o.x = pk2(acc[0], acc[1]); o.y = pk2(acc[2], acc[3]); o.z = pk2(acc[4], acc[5]); o.w = pk2(acc[6], acc[7]);
;                 *(LAS u32x4*)(xs + tok * 72 + ch) = o; }
.LBB0_186:
	s_ashr_i32 s50, s17, 3
	s_lshl_b32 s40, s50, 8
	s_and_b32 s1, s17, 7
	s_add_i32 s40, s40, s2
	s_cmp_lt_i32 s40, 0x10000
	s_movk_i32 s10, 0x100
	s_mov_b32 s11, 0x7fffff00
	s_cselect_b32 s10, 0x2000, s10
	s_cselect_b32 s11, 0xffffe000, s11
	s_lshl_b32 s19, s1, 6
	v_or_b32_e32 v12, s19, v127
	v_lshlrev_b32_e32 v14, 2, v12
	s_and_b32 s24, s11, s40
	s_add_i32 s25, s24, s10
	v_add_u32_e32 v16, s40, v128
	v_mov_b32_e32 v10, v14
	v_mov_b32_e32 v11, v0
	v_lshlrev_b32_e32 v12, 1, v12
	v_mov_b32_e32 v13, v0
	v_add_u32_e32 v17, 1, v16
	v_add_u32_e32 v18, 2, v16
	v_add_u32_e32 v19, 3, v16
	s_waitcnt lgkmcnt(0)
	v_lshl_add_u64 v[12:13], s[74:75], 0, v[12:13]
	v_lshl_add_u64 v[10:11], s[82:83], 0, v[10:11]
	v_mad_i64_i32 v[100:101], s[56:57], v16, s28, v[12:13]
	v_mad_i64_i32 v[102:103], s[56:57], v17, s28, v[12:13]
	v_mad_i64_i32 v[104:105], s[56:57], v18, s28, v[12:13]
	v_mad_i64_i32 v[106:107], s[56:57], v19, s28, v[12:13]
	v_lshl_add_u64 v[108:109], v[10:11], 0, s[54:55]
	v_cmp_le_i32_e32 vcc, s24, v16
	v_cmp_gt_i32_e64 s[10:11], s25, v16
	s_and_b64 s[92:93], vcc, s[10:11]
	v_cmp_le_i32_e32 vcc, s24, v17
	v_cmp_gt_i32_e64 s[10:11], s25, v17
	s_and_b64 s[96:97], vcc, s[10:11]
	v_cmp_le_i32_e32 vcc, s24, v18
	v_cmp_gt_i32_e64 s[10:11], s25, v18
	s_and_b64 s[94:95], vcc, s[10:11]
	v_cmp_le_i32_e32 vcc, s24, v19
	v_cmp_gt_i32_e64 s[10:11], s25, v19
	s_and_b64 s[22:23], vcc, s[10:11]
	global_load_dwordx4 v[2:5], v14, s[84:85] offset:16
	global_load_dwordx4 v[6:9], v14, s[84:85] offset:0
	global_load_dwordx4 v[20:23], v[100:101], off offset:0
	global_load_dwordx4 v[24:27], v[102:103], off offset:0
	global_load_dwordx4 v[28:31], v[104:105], off offset:0
	global_load_dwordx4 v[32:35], v[106:107], off offset:0
	global_load_dwordx4 v[36:39], v[10:11], off offset:0
	global_load_dwordx4 v[52:55], v[10:11], off offset:16
	global_load_dwordx4 v[40:43], v[10:11], off offset:2048
	global_load_dwordx4 v[56:59], v[10:11], off offset:2064
	global_load_dwordx4 v[44:47], v[108:109], off offset:0
	global_load_dwordx4 v[60:63], v[108:109], off offset:16
	global_load_dwordx4 v[48:51], v[108:109], off offset:2048
	global_load_dwordx4 v[64:67], v[108:109], off offset:2064
	s_waitcnt vmcnt(0)
	v_cndmask_b32_e64 v20, 0, v20, s[92:93]
	v_lshlrev_b32_e32 v68, 16, v20
	v_and_b32_e32 v69, 0xffff0000, v20
	v_pk_fma_f32 v[6:7], v[36:37], v[68:69], v[6:7]
	v_cndmask_b32_e64 v21, 0, v21, s[92:93]
	v_lshlrev_b32_e32 v68, 16, v21
	v_and_b32_e32 v69, 0xffff0000, v21
	v_pk_fma_f32 v[8:9], v[38:39], v[68:69], v[8:9]
	v_cndmask_b32_e64 v22, 0, v22, s[92:93]
	v_lshlrev_b32_e32 v68, 16, v22
	v_and_b32_e32 v69, 0xffff0000, v22
	v_pk_fma_f32 v[2:3], v[52:53], v[68:69], v[2:3]
	v_cndmask_b32_e64 v23, 0, v23, s[92:93]
	v_lshlrev_b32_e32 v68, 16, v23
	v_and_b32_e32 v69, 0xffff0000, v23
	v_pk_fma_f32 v[4:5], v[54:55], v[68:69], v[4:5]
	v_cndmask_b32_e64 v24, 0, v24, s[96:97]
	v_lshlrev_b32_e32 v68, 16, v24
	v_and_b32_e32 v69, 0xffff0000, v24
	v_pk_fma_f32 v[6:7], v[40:41], v[68:69], v[6:7]
	v_cndmask_b32_e64 v25, 0, v25, s[96:97]
	v_lshlrev_b32_e32 v68, 16, v25
	v_and_b32_e32 v69, 0xffff0000, v25
	v_pk_fma_f32 v[8:9], v[42:43], v[68:69], v[8:9]
	v_cndmask_b32_e64 v26, 0, v26, s[96:97]
	v_lshlrev_b32_e32 v68, 16, v26
	v_and_b32_e32 v69, 0xffff0000, v26
	v_pk_fma_f32 v[2:3], v[56:57], v[68:69], v[2:3]
	v_cndmask_b32_e64 v27, 0, v27, s[96:97]
	v_lshlrev_b32_e32 v68, 16, v27
	v_and_b32_e32 v69, 0xffff0000, v27
	v_pk_fma_f32 v[4:5], v[58:59], v[68:69], v[4:5]
	v_cndmask_b32_e64 v28, 0, v28, s[94:95]
	v_lshlrev_b32_e32 v68, 16, v28
	v_and_b32_e32 v69, 0xffff0000, v28
	v_pk_fma_f32 v[6:7], v[44:45], v[68:69], v[6:7]
	v_cndmask_b32_e64 v29, 0, v29, s[94:95]
	v_lshlrev_b32_e32 v68, 16, v29
	v_and_b32_e32 v69, 0xffff0000, v29
	v_pk_fma_f32 v[8:9], v[46:47], v[68:69], v[8:9]
	v_cndmask_b32_e64 v30, 0, v30, s[94:95]
	v_lshlrev_b32_e32 v68, 16, v30
	v_and_b32_e32 v69, 0xffff0000, v30
	v_pk_fma_f32 v[2:3], v[60:61], v[68:69], v[2:3]
	v_cndmask_b32_e64 v31, 0, v31, s[94:95]
	v_lshlrev_b32_e32 v68, 16, v31
	v_and_b32_e32 v69, 0xffff0000, v31
	v_pk_fma_f32 v[4:5], v[62:63], v[68:69], v[4:5]
	v_cndmask_b32_e64 v32, 0, v32, s[22:23]
	v_lshlrev_b32_e32 v68, 16, v32
	v_and_b32_e32 v69, 0xffff0000, v32
	v_pk_fma_f32 v[6:7], v[48:49], v[68:69], v[6:7]
	v_cndmask_b32_e64 v33, 0, v33, s[22:23]
	v_lshlrev_b32_e32 v68, 16, v33
	v_and_b32_e32 v69, 0xffff0000, v33
	v_pk_fma_f32 v[8:9], v[50:51], v[68:69], v[8:9]
	v_cndmask_b32_e64 v34, 0, v34, s[22:23]
	v_lshlrev_b32_e32 v68, 16, v34
	v_and_b32_e32 v69, 0xffff0000, v34
	v_pk_fma_f32 v[2:3], v[64:65], v[68:69], v[2:3]
	v_cndmask_b32_e64 v35, 0, v35, s[22:23]
	v_lshlrev_b32_e32 v68, 16, v35
	v_and_b32_e32 v69, 0xffff0000, v35
	v_pk_fma_f32 v[4:5], v[66:67], v[68:69], v[4:5]
	v_cvt_pk_bf16_f32 v6, v6, v7
	v_cvt_pk_bf16_f32 v7, v8, v9
	v_cvt_pk_bf16_f32 v8, v2, v3
	v_cvt_pk_bf16_f32 v9, v4, v5
	ds_write_b128 v131, v[6:9]
	global_load_dwordx4 v[2:5], v14, s[84:85] offset:48
	global_load_dwordx4 v[6:9], v14, s[84:85] offset:32
	global_load_dwordx4 v[20:23], v[100:101], off offset:16
	global_load_dwordx4 v[24:27], v[102:103], off offset:16
	global_load_dwordx4 v[28:31], v[104:105], off offset:16
	global_load_dwordx4 v[32:35], v[106:107], off offset:16
	global_load_dwordx4 v[36:39], v[10:11], off offset:32
	global_load_dwordx4 v[52:55], v[10:11], off offset:48
	global_load_dwordx4 v[40:43], v[10:11], off offset:2080
	global_load_dwordx4 v[56:59], v[10:11], off offset:2096
	global_load_dwordx4 v[44:47], v[108:109], off offset:32
	global_load_dwordx4 v[60:63], v[108:109], off offset:48
	global_load_dwordx4 v[48:51], v[108:109], off offset:2080
	global_load_dwordx4 v[64:67], v[108:109], off offset:2096
	s_waitcnt vmcnt(0)
; #define LAS __attribute__((address_space(3)))
; #define GAS __attribute__((address_space(1)))
; __device__ __forceinline__ unsigned pk2(float lo, float hi) { return cvtpk(lo, hi); }
; __device__ __forceinline__ float bflo(unsigned w) { return __uint_as_float(w << 16); }
; __device__ __forceinline__ float bfhi(unsigned w) { return __uint_as_float(w & 0xffff0000u); }
; __device__ __forceinline__ void gates_phase(const GAS float* __restrict__ cw, const GAS float* __restrict__ cb, const GAS float* __restrict__ b_a, const GAS float* __restrict__ b_x, const GAS float* __restrict__ lam, LAS unsigned char* lds, const GAS bf16_t* __restrict__ P, const GAS bf16_t* __restr ...
;     ...
;             for (int c8 = 0; c8 < 4; ++c8) { const int ch = (lane & 1) * 32 + c8 * 8, gch = h * 64 + ch;
;                 float acc[8];
;                 { const f32x4 b0 = *(const GAS f32x4*)(cb + gch), b1 = *(const GAS f32x4*)(cb + gch + 4);
;                   acc[0] = b0.x; acc[1] = b0.y; acc[2] = b0.z; acc[3] = b0.w; acc[4] = b1.x; acc[5] = b1.y; acc[6] = b1.z; acc[7] = b1.w; }
; #pragma unroll
;                 for (int k = 0; k < 4; ++k) { const int mm = m + k - 2;
;                     if (mm >= s0 && mm < s0 + slen) { const u32x4 xv = *(const GAS u32x4*)(P + (size_t)mm * PW + gch);
;                         const f32x4 w0 = *(const GAS f32x4*)(cw + k * 512 + gch), w1 = *(const GAS f32x4*)(cw + k * 512 + gch + 4);
;                         acc[0] += w0.x * bflo(xv.x); acc[1] += w0.y * bfhi(xv.x); acc[2] += w0.z * bflo(xv.y); acc[3] += w0.w * bfhi(xv.y);
;                         acc[4] += w1.x * bflo(xv.z); acc[5] += w1.y * bfhi(xv.z); acc[6] += w1.z * bflo(xv.w); acc[7] += w1.w * bfhi(xv.w); } }
;                 u32x4 o; o.x = pk2(acc[0], acc[1]); o.y = pk2(acc[2], acc[3]); o.z = pk2(acc[4], acc[5]); o.w = pk2(acc[6], acc[7]);
;                 *(LAS u32x4*)(xs + tok * 72 + ch) = o; }
	v_cndmask_b32_e64 v20, 0, v20, s[92:93]
	v_lshlrev_b32_e32 v68, 16, v20
	v_and_b32_e32 v69, 0xffff0000, v20
	v_pk_fma_f32 v[6:7], v[36:37], v[68:69], v[6:7]
	v_cndmask_b32_e64 v21, 0, v21, s[92:93]
	v_lshlrev_b32_e32 v68, 16, v21
	v_and_b32_e32 v69, 0xffff0000, v21
	v_pk_fma_f32 v[8:9], v[38:39], v[68:69], v[8:9]
	v_cndmask_b32_e64 v22, 0, v22, s[92:93]
	v_lshlrev_b32_e32 v68, 16, v22
	v_and_b32_e32 v69, 0xffff0000, v22
	v_pk_fma_f32 v[2:3], v[52:53], v[68:69], v[2:3]
	v_cndmask_b32_e64 v23, 0, v23, s[92:93]
	v_lshlrev_b32_e32 v68, 16, v23
	v_and_b32_e32 v69, 0xffff0000, v23
	v_pk_fma_f32 v[4:5], v[54:55], v[68:69], v[4:5]
	v_cndmask_b32_e64 v24, 0, v24, s[96:97]
	v_lshlrev_b32_e32 v68, 16, v24
	v_and_b32_e32 v69, 0xffff0000, v24
	v_pk_fma_f32 v[6:7], v[40:41], v[68:69], v[6:7]
	v_cndmask_b32_e64 v25, 0, v25, s[96:97]
	v_lshlrev_b32_e32 v68, 16, v25
	v_and_b32_e32 v69, 0xffff0000, v25
	v_pk_fma_f32 v[8:9], v[42:43], v[68:69], v[8:9]
	v_cndmask_b32_e64 v26, 0, v26, s[96:97]
	v_lshlrev_b32_e32 v68, 16, v26
	v_and_b32_e32 v69, 0xffff0000, v26
	v_pk_fma_f32 v[2:3], v[56:57], v[68:69], v[2:3]
	v_cndmask_b32_e64 v27, 0, v27, s[96:97]
	v_lshlrev_b32_e32 v68, 16, v27
	v_and_b32_e32 v69, 0xffff0000, v27
	v_pk_fma_f32 v[4:5], v[58:59], v[68:69], v[4:5]
	v_cndmask_b32_e64 v28, 0, v28, s[94:95]
	v_lshlrev_b32_e32 v68, 16, v28
	v_and_b32_e32 v69, 0xffff0000, v28
	v_pk_fma_f32 v[6:7], v[44:45], v[68:69], v[6:7]
	v_cndmask_b32_e64 v29, 0, v29, s[94:95]
	v_lshlrev_b32_e32 v68, 16, v29
	v_and_b32_e32 v69, 0xffff0000, v29
	v_pk_fma_f32 v[8:9], v[46:47], v[68:69], v[8:9]
	v_cndmask_b32_e64 v30, 0, v30, s[94:95]
	v_lshlrev_b32_e32 v68, 16, v30
	v_and_b32_e32 v69, 0xffff0000, v30
	v_pk_fma_f32 v[2:3], v[60:61], v[68:69], v[2:3]
	v_cndmask_b32_e64 v31, 0, v31, s[94:95]
	v_lshlrev_b32_e32 v68, 16, v31
	v_and_b32_e32 v69, 0xffff0000, v31
	v_pk_fma_f32 v[4:5], v[62:63], v[68:69], v[4:5]
	v_cndmask_b32_e64 v32, 0, v32, s[22:23]
	v_lshlrev_b32_e32 v68, 16, v32
	v_and_b32_e32 v69, 0xffff0000, v32
	v_pk_fma_f32 v[6:7], v[48:49], v[68:69], v[6:7]
	v_cndmask_b32_e64 v33, 0, v33, s[22:23]
	v_lshlrev_b32_e32 v68, 16, v33
	v_and_b32_e32 v69, 0xffff0000, v33
	v_pk_fma_f32 v[8:9], v[50:51], v[68:69], v[8:9]
	v_cndmask_b32_e64 v34, 0, v34, s[22:23]
	v_lshlrev_b32_e32 v68, 16, v34
	v_and_b32_e32 v69, 0xffff0000, v34
	v_pk_fma_f32 v[2:3], v[64:65], v[68:69], v[2:3]
	v_cndmask_b32_e64 v35, 0, v35, s[22:23]
	v_lshlrev_b32_e32 v68, 16, v35
	v_and_b32_e32 v69, 0xffff0000, v35
	v_pk_fma_f32 v[4:5], v[66:67], v[68:69], v[4:5]
	v_cvt_pk_bf16_f32 v6, v6, v7
	v_cvt_pk_bf16_f32 v7, v8, v9
	v_cvt_pk_bf16_f32 v8, v2, v3
	v_cvt_pk_bf16_f32 v9, v4, v5
	ds_write_b128 v131, v[6:9] offset:16
	global_load_dwordx4 v[2:5], v14, s[84:85] offset:80
	global_load_dwordx4 v[6:9], v14, s[84:85] offset:64
	global_load_dwordx4 v[20:23], v[100:101], off offset:32
	global_load_dwordx4 v[24:27], v[102:103], off offset:32
	global_load_dwordx4 v[28:31], v[104:105], off offset:32
	global_load_dwordx4 v[32:35], v[106:107], off offset:32
	global_load_dwordx4 v[36:39], v[10:11], off offset:64
	global_load_dwordx4 v[52:55], v[10:11], off offset:80
	global_load_dwordx4 v[40:43], v[10:11], off offset:2112
	global_load_dwordx4 v[56:59], v[10:11], off offset:2128
	global_load_dwordx4 v[44:47], v[108:109], off offset:64
	global_load_dwordx4 v[60:63], v[108:109], off offset:80
	global_load_dwordx4 v[48:51], v[108:109], off offset:2112
	global_load_dwordx4 v[64:67], v[108:109], off offset:2128
	s_waitcnt vmcnt(0)
	v_cndmask_b32_e64 v20, 0, v20, s[92:93]
	v_lshlrev_b32_e32 v68, 16, v20
	v_and_b32_e32 v69, 0xffff0000, v20
	v_pk_fma_f32 v[6:7], v[36:37], v[68:69], v[6:7]
	v_cndmask_b32_e64 v21, 0, v21, s[92:93]
	v_lshlrev_b32_e32 v68, 16, v21
	v_and_b32_e32 v69, 0xffff0000, v21
	v_pk_fma_f32 v[8:9], v[38:39], v[68:69], v[8:9]
	v_cndmask_b32_e64 v22, 0, v22, s[92:93]
	v_lshlrev_b32_e32 v68, 16, v22
	v_and_b32_e32 v69, 0xffff0000, v22
	v_pk_fma_f32 v[2:3], v[52:53], v[68:69], v[2:3]
	v_cndmask_b32_e64 v23, 0, v23, s[92:93]
	v_lshlrev_b32_e32 v68, 16, v23
	v_and_b32_e32 v69, 0xffff0000, v23
	v_pk_fma_f32 v[4:5], v[54:55], v[68:69], v[4:5]
	v_cndmask_b32_e64 v24, 0, v24, s[96:97]
	v_lshlrev_b32_e32 v68, 16, v24
	v_and_b32_e32 v69, 0xffff0000, v24
	v_pk_fma_f32 v[6:7], v[40:41], v[68:69], v[6:7]
	v_cndmask_b32_e64 v25, 0, v25, s[96:97]
	v_lshlrev_b32_e32 v68, 16, v25
	v_and_b32_e32 v69, 0xffff0000, v25
	v_pk_fma_f32 v[8:9], v[42:43], v[68:69], v[8:9]
	v_cndmask_b32_e64 v26, 0, v26, s[96:97]
	v_lshlrev_b32_e32 v68, 16, v26
	v_and_b32_e32 v69, 0xffff0000, v26
	v_pk_fma_f32 v[2:3], v[56:57], v[68:69], v[2:3]
	v_cndmask_b32_e64 v27, 0, v27, s[96:97]
	v_lshlrev_b32_e32 v68, 16, v27
	v_and_b32_e32 v69, 0xffff0000, v27
	v_pk_fma_f32 v[4:5], v[58:59], v[68:69], v[4:5]
	v_cndmask_b32_e64 v28, 0, v28, s[94:95]
	v_lshlrev_b32_e32 v68, 16, v28
	v_and_b32_e32 v69, 0xffff0000, v28
	v_pk_fma_f32 v[6:7], v[44:45], v[68:69], v[6:7]
	v_cndmask_b32_e64 v29, 0, v29, s[94:95]
	v_lshlrev_b32_e32 v68, 16, v29
	v_and_b32_e32 v69, 0xffff0000, v29
	v_pk_fma_f32 v[8:9], v[46:47], v[68:69], v[8:9]
	v_cndmask_b32_e64 v30, 0, v30, s[94:95]
	v_lshlrev_b32_e32 v68, 16, v30
	v_and_b32_e32 v69, 0xffff0000, v30
	v_pk_fma_f32 v[2:3], v[60:61], v[68:69], v[2:3]
	v_cndmask_b32_e64 v31, 0, v31, s[94:95]
	v_lshlrev_b32_e32 v68, 16, v31
	v_and_b32_e32 v69, 0xffff0000, v31
	v_pk_fma_f32 v[4:5], v[62:63], v[68:69], v[4:5]
	v_cndmask_b32_e64 v32, 0, v32, s[22:23]
	v_lshlrev_b32_e32 v68, 16, v32
	v_and_b32_e32 v69, 0xffff0000, v32
	v_pk_fma_f32 v[6:7], v[48:49], v[68:69], v[6:7]
	v_cndmask_b32_e64 v33, 0, v33, s[22:23]
	v_lshlrev_b32_e32 v68, 16, v33
	v_and_b32_e32 v69, 0xffff0000, v33
	v_pk_fma_f32 v[8:9], v[50:51], v[68:69], v[8:9]
	v_cndmask_b32_e64 v34, 0, v34, s[22:23]
	v_lshlrev_b32_e32 v68, 16, v34
	v_and_b32_e32 v69, 0xffff0000, v34
	v_pk_fma_f32 v[2:3], v[64:65], v[68:69], v[2:3]
	v_cndmask_b32_e64 v35, 0, v35, s[22:23]
	v_lshlrev_b32_e32 v68, 16, v35
	v_and_b32_e32 v69, 0xffff0000, v35
	v_pk_fma_f32 v[4:5], v[66:67], v[68:69], v[4:5]
	v_cvt_pk_bf16_f32 v6, v6, v7
	v_cvt_pk_bf16_f32 v7, v8, v9
	v_cvt_pk_bf16_f32 v8, v2, v3
	v_cvt_pk_bf16_f32 v9, v4, v5
	ds_write_b128 v131, v[6:9] offset:32
	global_load_dwordx4 v[2:5], v14, s[84:85] offset:112
	global_load_dwordx4 v[6:9], v14, s[84:85] offset:96
	global_load_dwordx4 v[20:23], v[100:101], off offset:48
	global_load_dwordx4 v[24:27], v[102:103], off offset:48
	global_load_dwordx4 v[28:31], v[104:105], off offset:48
	global_load_dwordx4 v[32:35], v[106:107], off offset:48
	global_load_dwordx4 v[36:39], v[10:11], off offset:96
	global_load_dwordx4 v[52:55], v[10:11], off offset:112
	global_load_dwordx4 v[40:43], v[10:11], off offset:2144
	global_load_dwordx4 v[56:59], v[10:11], off offset:2160
	global_load_dwordx4 v[44:47], v[108:109], off offset:96
	global_load_dwordx4 v[60:63], v[108:109], off offset:112
	global_load_dwordx4 v[48:51], v[108:109], off offset:2144
	global_load_dwordx4 v[64:67], v[108:109], off offset:2160
	s_waitcnt vmcnt(0)
; #define LAS __attribute__((address_space(3)))
; #define GAS __attribute__((address_space(1)))
; __device__ __forceinline__ unsigned pk2(float lo, float hi) { return cvtpk(lo, hi); }
; __device__ __forceinline__ void gates_phase(const GAS float* __restrict__ cw, const GAS float* __restrict__ cb, const GAS float* __restrict__ b_a, const GAS float* __restrict__ b_x, const GAS float* __restrict__ lam, LAS unsigned char* lds, const GAS bf16_t* __restrict__ P, const GAS bf16_t* __restr ...
;     ...
;             for (int c8 = 0; c8 < 4; ++c8) { const int ch = (lane & 1) * 32 + c8 * 8, gch = h * 64 + ch;
;                 float acc[8];
;                 { const f32x4 b0 = *(const GAS f32x4*)(cb + gch), b1 = *(const GAS f32x4*)(cb + gch + 4);
;                   acc[0] = b0.x; acc[1] = b0.y; acc[2] = b0.z; acc[3] = b0.w; acc[4] = b1.x; acc[5] = b1.y; acc[6] = b1.z; acc[7] = b1.w; }
; #pragma unroll
;                 for (int k = 0; k < 4; ++k) { const int mm = m + k - 2;
;                     if (mm >= s0 && mm < s0 + slen) { const u32x4 xv = *(const GAS u32x4*)(P + (size_t)mm * PW + gch);
;                         const f32x4 w0 = *(const GAS f32x4*)(cw + k * 512 + gch), w1 = *(const GAS f32x4*)(cw + k * 512 + gch + 4);
;                         acc[0] += w0.x * bflo(xv.x); acc[1] += w0.y * bfhi(xv.x); acc[2] += w0.z * bflo(xv.y); acc[3] += w0.w * bfhi(xv.y);
;                         acc[4] += w1.x * bflo(xv.z); acc[5] += w1.y * bfhi(xv.z); acc[6] += w1.z * bflo(xv.w); acc[7] += w1.w * bfhi(xv.w); } }
;                 u32x4 o; o.x = pk2(acc[0], acc[1]); o.y = pk2(acc[2], acc[3]); o.z = pk2(acc[4], acc[5]); o.w = pk2(acc[6], acc[7]);
;                 *(LAS u32x4*)(xs + tok * 72 + ch) = o; }
;         }
;         LDS_WAIT();
;         bf16x8 afr[4];
; #pragma unroll
;         for (int ks = 0; ks < 4; ++ks) afr[ks] = *(const LAS bf16x8*)(xs + r32 * 72 + 16 * ks + 8 * hi);
; #pragma unroll
;         for (int jh = 0; jh < 2; ++jh) {
;             f32x16 acc4[4];
; #pragma unroll
;             for (int q = 0; q < 4; ++q) {
; #pragma unroll
;                 for (int i = 0; i < 16; ++i) acc4[q][i] = 0.f;
;                 const GAS bf16_t* wrow = Wg + (size_t)(h * 256 + (2 * q + jh) * 32 + r32) * 64 + 8 * hi;
; #pragma unroll
;                 for (int ks = 0; ks < 4; ++ks) { const bf16x8 bfr = *(const GAS bf16x8*)(wrow + 16 * ks); acc4[q] = MFMA32(afr[ks], bfr, acc4[q]); }
	v_cndmask_b32_e64 v20, 0, v20, s[92:93]
	v_lshlrev_b32_e32 v68, 16, v20
	v_and_b32_e32 v69, 0xffff0000, v20
	v_pk_fma_f32 v[6:7], v[36:37], v[68:69], v[6:7]
	v_cndmask_b32_e64 v21, 0, v21, s[92:93]
	v_lshlrev_b32_e32 v68, 16, v21
	v_and_b32_e32 v69, 0xffff0000, v21
	v_pk_fma_f32 v[8:9], v[38:39], v[68:69], v[8:9]
	v_cndmask_b32_e64 v22, 0, v22, s[92:93]
	v_lshlrev_b32_e32 v68, 16, v22
	v_and_b32_e32 v69, 0xffff0000, v22
	v_pk_fma_f32 v[2:3], v[52:53], v[68:69], v[2:3]
	v_cndmask_b32_e64 v23, 0, v23, s[92:93]
	v_lshlrev_b32_e32 v68, 16, v23
	v_and_b32_e32 v69, 0xffff0000, v23
	v_pk_fma_f32 v[4:5], v[54:55], v[68:69], v[4:5]
	v_cndmask_b32_e64 v24, 0, v24, s[96:97]
	v_lshlrev_b32_e32 v68, 16, v24
	v_and_b32_e32 v69, 0xffff0000, v24
	v_pk_fma_f32 v[6:7], v[40:41], v[68:69], v[6:7]
	v_cndmask_b32_e64 v25, 0, v25, s[96:97]
	v_lshlrev_b32_e32 v68, 16, v25
	v_and_b32_e32 v69, 0xffff0000, v25
	v_pk_fma_f32 v[8:9], v[42:43], v[68:69], v[8:9]
	v_cndmask_b32_e64 v26, 0, v26, s[96:97]
	v_lshlrev_b32_e32 v68, 16, v26
	v_and_b32_e32 v69, 0xffff0000, v26
	v_pk_fma_f32 v[2:3], v[56:57], v[68:69], v[2:3]
	v_cndmask_b32_e64 v27, 0, v27, s[96:97]
	v_lshlrev_b32_e32 v68, 16, v27
	v_and_b32_e32 v69, 0xffff0000, v27
	v_pk_fma_f32 v[4:5], v[58:59], v[68:69], v[4:5]
	v_cndmask_b32_e64 v28, 0, v28, s[94:95]
	v_lshlrev_b32_e32 v68, 16, v28
	v_and_b32_e32 v69, 0xffff0000, v28
	v_pk_fma_f32 v[6:7], v[44:45], v[68:69], v[6:7]
	v_cndmask_b32_e64 v29, 0, v29, s[94:95]
	v_lshlrev_b32_e32 v68, 16, v29
	v_and_b32_e32 v69, 0xffff0000, v29
	v_pk_fma_f32 v[8:9], v[46:47], v[68:69], v[8:9]
	v_cndmask_b32_e64 v30, 0, v30, s[94:95]
	v_lshlrev_b32_e32 v68, 16, v30
	v_and_b32_e32 v69, 0xffff0000, v30
	v_pk_fma_f32 v[2:3], v[60:61], v[68:69], v[2:3]
	v_cndmask_b32_e64 v31, 0, v31, s[94:95]
	v_lshlrev_b32_e32 v68, 16, v31
	v_and_b32_e32 v69, 0xffff0000, v31
	v_pk_fma_f32 v[4:5], v[62:63], v[68:69], v[4:5]
	v_cndmask_b32_e64 v32, 0, v32, s[22:23]
	v_lshlrev_b32_e32 v68, 16, v32
	v_and_b32_e32 v69, 0xffff0000, v32
	v_pk_fma_f32 v[6:7], v[48:49], v[68:69], v[6:7]
	v_cndmask_b32_e64 v33, 0, v33, s[22:23]
	v_lshlrev_b32_e32 v68, 16, v33
	v_and_b32_e32 v69, 0xffff0000, v33
	v_pk_fma_f32 v[8:9], v[50:51], v[68:69], v[8:9]
	v_cndmask_b32_e64 v34, 0, v34, s[22:23]
	v_lshlrev_b32_e32 v68, 16, v34
	v_and_b32_e32 v69, 0xffff0000, v34
	v_pk_fma_f32 v[2:3], v[64:65], v[68:69], v[2:3]
	v_cndmask_b32_e64 v35, 0, v35, s[22:23]
	v_lshlrev_b32_e32 v68, 16, v35
	v_and_b32_e32 v69, 0xffff0000, v35
	v_pk_fma_f32 v[4:5], v[66:67], v[68:69], v[4:5]
	v_cvt_pk_bf16_f32 v6, v6, v7
	v_cvt_pk_bf16_f32 v7, v8, v9
	v_cvt_pk_bf16_f32 v8, v2, v3
	v_lshl_or_b32 v2, s1, 15, v163
	v_mov_b32_e32 v3, v0
	v_cvt_pk_bf16_f32 v9, v4, v5
	v_lshl_add_u64 v[114:115], v[96:97], 0, v[2:3]
	ds_write_b128 v131, v[6:9] offset:48
	v_add_co_u32_e32 v82, vcc, s68, v114
	s_waitcnt lgkmcnt(0)
	global_load_dwordx4 v[2:5], v[114:115], off
	s_nop 0
	v_addc_co_u32_e32 v83, vcc, 0, v115, vcc
	v_add_co_u32_e32 v84, vcc, s70, v114
	global_load_dwordx4 v[6:9], v[82:83], off
	s_nop 0
	v_addc_co_u32_e32 v85, vcc, 0, v115, vcc
	global_load_dwordx4 v[10:13], v[84:85], off
	v_add_co_u32_e32 v112, vcc, s46, v114
	v_add_u32_e32 v99, v129, v94
	s_nop 0
	v_addc_co_u32_e32 v113, vcc, 0, v115, vcc
	global_load_dwordx4 v[14:17], v[112:113], off
	global_load_dwordx4 v[74:77], v[114:115], off offset:32
	global_load_dwordx4 v[78:81], v[82:83], off offset:32
	global_load_dwordx4 v[90:93], v[112:113], off offset:32
	global_load_dwordx4 v[108:111], v[84:85], off offset:64
	global_load_dwordx4 v[86:89], v[84:85], off offset:32
	global_load_dwordx4 v[104:107], v[82:83], off offset:64
	ds_read_b128 v[70:73], v99
	ds_read_b128 v[66:69], v99 offset:32
	global_load_dwordx4 v[100:103], v[114:115], off offset:64
	global_load_dwordx4 v[116:119], v[114:115], off offset:96
	global_load_dwordx4 v[178:181], v[82:83], off offset:96
	s_nop 0
	global_load_dwordx4 v[82:85], v[84:85], off offset:96
	v_mov_b32_e32 v121, v0
	s_waitcnt vmcnt(13) lgkmcnt(1)
	v_mfma_f32_32x32x16_bf16 v[50:65], v[70:73], v[2:5], 0
	s_waitcnt vmcnt(12)
	v_mfma_f32_32x32x16_bf16 v[34:49], v[70:73], v[6:9], 0
	s_waitcnt vmcnt(11)
	v_mfma_f32_32x32x16_bf16 v[18:33], v[70:73], v[10:13], 0
	s_waitcnt vmcnt(10)
	v_mfma_f32_32x32x16_bf16 v[2:17], v[70:73], v[14:17], 0
	s_waitcnt vmcnt(9) lgkmcnt(0)
	v_mfma_f32_32x32x16_bf16 v[50:65], v[66:69], v[74:77], v[50:65]
	v_or_b32_e32 v74, s19, v1
	v_lshlrev_b32_e32 v120, 2, v74
	global_load_dword v177, v120, s[86:87]
	global_load_dword v175, v120, s[88:89]
	global_load_dword v172, v120, s[88:89] offset:2048
	global_load_dword v173, v120, s[86:87] offset:2048
	global_load_dword v176, v120, s[90:91]
	ds_read_b128 v[74:77], v99 offset:64
	v_lshl_add_u64 v[122:123], s[76:77], 0, v[120:121]
	s_waitcnt vmcnt(12)
	v_mfma_f32_32x32x16_bf16 v[2:17], v[66:69], v[90:93], v[2:17]
	global_load_dwordx4 v[90:93], v[112:113], off offset:64
	s_waitcnt vmcnt(11)
	v_mfma_f32_32x32x16_bf16 v[18:33], v[66:69], v[86:89], v[18:33]
	global_load_dwordx4 v[86:89], v[112:113], off offset:96
	v_mfma_f32_32x32x16_bf16 v[34:49], v[66:69], v[78:81], v[34:49]
	ds_read_b128 v[78:81], v99 offset:96
	v_or_b32_e32 v99, 0x800, v120
	global_load_dword v174, v99, s[90:91]
	v_xor_b32_e32 v99, 32, v186
	s_waitcnt vmcnt(11) lgkmcnt(1)
	v_mfma_f32_32x32x16_bf16 v[50:65], v[74:77], v[100:103], v[50:65]
	v_and_b32_e32 v101, 64, v186
	v_or_b32_e32 v102, s40, v95
	v_add_u32_e32 v101, 64, v101
	v_ashrrev_i32_e32 v103, 31, v102
	v_add_u32_e32 v100, v135, v138
	v_cmp_lt_i32_e32 vcc, v99, v101
	s_waitcnt vmcnt(10) lgkmcnt(0)
; #define GAS __attribute__((address_space(1)))
; __device__ __forceinline__ unsigned f2bf(float f) { unsigned u = __builtin_bit_cast(unsigned, f); return (u + 0x7fffu + ((u >> 16) & 1u)) >> 16; }
; __device__ __forceinline__ unsigned pk2(float lo, float hi) { return cvtpk(lo, hi); }
; __device__ __forceinline__ float bflo(unsigned w) { return __uint_as_float(w << 16); }
; __device__ __forceinline__ float bf2f(bf16_t v) { return __uint_as_float((unsigned)v << 16); }
; __device__ __forceinline__ int crow(int r, int hi) { return (r & 3) + 8 * (r >> 2) + 4 * hi; }
; __device__ __forceinline__ float sigmoidf_(float x) { return __builtin_amdgcn_rcpf(1.f + __builtin_amdgcn_exp2f(-1.4426950408889634f * x)); }
; #define MFMA32(a, b, c) __builtin_amdgcn_mfma_f32_32x32x16_bf16((a), (b), (c), 0, 0, 0)
; __device__ __forceinline__ void gates_phase(const GAS float* __restrict__ cw, const GAS float* __restrict__ cb, const GAS float* __restrict__ b_a, const GAS float* __restrict__ b_x, const GAS float* __restrict__ lam, LAS unsigned char* lds, const GAS bf16_t* __restrict__ P, const GAS bf16_t* __restr ...
;     ...
;                 for (int ks = 0; ks < 4; ++ks) { const bf16x8 bfr = *(const GAS bf16x8*)(wrow + 16 * ks); acc4[q] = MFMA32(afr[ks], bfr, acc4[q]); }
;             }
;             const int ch = jh * 32 + r32, gch = h * 64 + ch;
;             float ba[2], bx[2], sp[2];
; #pragma unroll
;             for (int d = 0; d < 2; ++d) { ba[d] = b_a[d * 512 + gch]; bx[d] = b_x[d * 512 + gch]; sp[d] = lam[d * 512 + gch]; }
;             unsigned wv[16][2]; float avs[16][2];
; #pragma unroll
;             for (int i = 0; i < 16; ++i) { const int row = crow(i, hi); const float xv = bf2f(xs[row * 72 + ch]);
; #pragma unroll
;                 for (int d = 0; d < 2; ++d) { const float r = sigmoidf_(acc4[2 * d][i] + ba[d]), ig = sigmoidf_(acc4[2 * d + 1][i] + bx[d]);
;                     const float la2 = bflo(f2bf(-r * sp[d])), av = __builtin_amdgcn_exp2f(la2); avs[i][d] = av;
;                     const float uu = __builtin_amdgcn_sqrtf(fmaxf(1.f - av * av, 0.f)) * (ig * xv);
;                     wv[i][d] = pk2(la2, uu);
;                     __builtin_nontemporal_store(wv[i][d], LU + ((size_t)(m0 + row) * 2 + d) * 512 + gch); } }
	v_mfma_f32_32x32x16_bf16 v[50:65], v[78:81], v[116:119], v[50:65]
	v_lshlrev_b64 v[118:119], 12, v[102:103]
	v_lshl_add_u64 v[124:125], v[122:123], 0, v[118:119]
	v_cndmask_b32_e32 v99, v186, v99, vcc
	v_lshlrev_b32_e32 v99, 2, v99
	v_mfma_f32_32x32x16_bf16 v[18:33], v[74:77], v[108:111], v[18:33]
	s_waitcnt vmcnt(7)
	s_nop 5
	v_add_f32_e32 v50, v50, v177
	s_waitcnt vmcnt(2)
	v_mfma_f32_32x32x16_bf16 v[2:17], v[74:77], v[90:93], v[2:17]
	v_mul_f32_e32 v50, 0xbfb8aa3b, v50
	v_exp_f32_e32 v50, v50
	s_nop 0
	v_add_f32_e32 v50, 1.0, v50
	v_rcp_f32_e64 v50, -v50
	s_waitcnt vmcnt(1)
	v_mfma_f32_32x32x16_bf16 v[2:17], v[78:81], v[86:89], v[2:17]
	v_mfma_f32_32x32x16_bf16 v[34:49], v[74:77], v[104:107], v[34:49]
	s_nop 10
	v_add_f32_e32 v2, v2, v172
	v_mul_f32_e32 v2, 0xbfb8aa3b, v2
	v_exp_f32_e32 v2, v2
	v_add_u32_e32 v104, v135, v136
	ds_read_u16 v101, v104
	ds_read_u16 v102, v100
	ds_read_u16 v103, v100 offset:144
	ds_read_u16 v104, v100 offset:288
	ds_read_u16 v105, v100 offset:1008
	ds_read_u16 v106, v100 offset:1152
	ds_read_u16 v107, v100 offset:1296
	ds_read_u16 v211, v100 offset:1440
	s_waitcnt lgkmcnt(6)
	v_lshlrev_b32_e32 v87, 16, v102
	v_add_f32_e32 v2, 1.0, v2
	v_mfma_f32_32x32x16_bf16 v[18:33], v[78:81], v[82:85], v[18:33]
	v_mul_f32_e32 v83, v176, v50
	v_add_f32_e32 v50, v51, v177
	v_mul_f32_e32 v50, 0xbfb8aa3b, v50
	v_exp_f32_e32 v51, v50
	v_rcp_f32_e32 v2, v2
	v_lshlrev_b32_e32 v82, 16, v101
	v_add_f32_e32 v3, v3, v172
	v_mfma_f32_32x32x16_bf16 v[34:49], v[78:81], v[178:181], v[34:49]
	s_nop 3
	v_add_f32_e32 v18, v18, v173
	v_add_f32_e32 v51, 1.0, v51
	v_mul_f32_e32 v18, 0xbfb8aa3b, v18
	v_rcp_f32_e64 v51, -v51
	v_mul_f32_e32 v84, v2, v82
	v_bfe_u32 v2, v83, 16, 1
	v_exp_f32_e32 v18, v18
	s_nop 0
	v_add_f32_e32 v34, v34, v175
	v_mul_f32_e32 v34, 0xbfb8aa3b, v34
	v_add3_u32 v2, v83, v2, s61
	v_exp_f32_e32 v34, v34
	v_add_f32_e32 v35, v35, v175
	v_and_b32_e32 v2, 0xffff0000, v2
	v_mul_f32_e32 v35, 0xbfb8aa3b, v35
	v_exp_f32_e32 v180, v2
	v_exp_f32_e32 v86, v35
	v_mul_f32_e32 v35, v176, v51
	v_add_f32_e32 v18, 1.0, v18
	v_bfe_u32 v51, v35, 16, 1
	v_add_f32_e32 v34, 1.0, v34
	v_rcp_f32_e64 v18, -v18
	v_add3_u32 v35, v35, v51, s61
	v_rcp_f32_e32 v34, v34
	v_and_b32_e32 v88, 0xffff0000, v35
	v_fma_f32 v35, -v180, v180, 1.0
	v_max_f32_e32 v35, 0, v35
	v_sqrt_f32_e32 v51, v35
	s_waitcnt vmcnt(0)
	v_mul_f32_e32 v18, v174, v18
	v_exp_f32_e32 v181, v88
	v_mul_f32_e32 v34, v34, v82
	v_bfe_u32 v82, v18, 16, 1
	v_add3_u32 v18, v18, v82, s61
	v_and_b32_e32 v85, 0xffff0000, v18
	v_mul_f32_e32 v18, v34, v51
	v_cvt_pk_bf16_f32 v182, v2, v18
	v_add_f32_e32 v2, 1.0, v86
	v_fma_f32 v18, -v181, v181, 1.0
	v_rcp_f32_e32 v2, v2
	v_max_f32_e32 v18, 0, v18
	v_sqrt_f32_e32 v18, v18
	v_mul_f32_e32 v3, 0xbfb8aa3b, v3
	v_mul_f32_e32 v2, v2, v87
	v_exp_f32_e32 v3, v3
	v_mul_f32_e32 v2, v2, v18
	v_cvt_pk_bf16_f32 v183, v88, v2
	v_add_f32_e32 v2, v19, v173
	v_mul_f32_e32 v2, 0xbfb8aa3b, v2
	v_exp_f32_e32 v2, v2
	v_add_f32_e32 v3, 1.0, v3
	v_add_f32_e32 v19, v52, v177
	v_rcp_f32_e32 v3, v3
	v_add_f32_e32 v2, 1.0, v2
	v_rcp_f32_e64 v2, -v2
	v_mul_f32_e32 v19, 0xbfb8aa3b, v19
	v_exp_f32_e32 v19, v19
	v_mul_f32_e32 v87, v3, v87
	v_mul_f32_e32 v2, v174, v2
	v_bfe_u32 v18, v2, 16, 1
	v_add3_u32 v2, v2, v18, s61
	v_and_b32_e32 v86, 0xffff0000, v2
	v_or_b32_e32 v2, s40, v139
	v_ashrrev_i32_e32 v3, 31, v2
	v_lshlrev_b64 v[116:117], 12, v[2:3]
	v_add_f32_e32 v2, 1.0, v19
	v_add_f32_e32 v19, v20, v173
	v_mul_f32_e32 v19, 0xbfb8aa3b, v19
	v_exp_f32_e32 v19, v19
	v_rcp_f32_e64 v2, -v2
	v_add_f32_e32 v4, v4, v172
	v_mul_f32_e32 v4, 0xbfb8aa3b, v4
	v_add_f32_e32 v19, 1.0, v19
	v_rcp_f32_e64 v19, -v19
	v_mul_f32_e32 v2, v176, v2
	v_bfe_u32 v20, v2, 16, 1
	v_add3_u32 v2, v2, v20, s61
	v_mul_f32_e32 v19, v174, v19
	v_bfe_u32 v20, v19, 16, 1
	v_add3_u32 v19, v19, v20, s61
	v_and_b32_e32 v20, 0xffff0000, v19
	v_add_f32_e32 v36, v36, v175
	v_exp_f32_e32 v4, v4
	v_exp_f32_e32 v52, v20
	v_mul_f32_e32 v36, 0xbfb8aa3b, v36
	v_exp_f32_e32 v36, v36
	v_and_b32_e32 v19, 0xffff0000, v2
	v_add_f32_e32 v2, 1.0, v4
	v_fma_f32 v4, -v52, v52, 1.0
	v_rcp_f32_e32 v2, v2
	v_max_f32_e32 v4, 0, v4
	v_add_f32_e32 v3, 1.0, v36
	v_sqrt_f32_e32 v36, v4
	s_waitcnt lgkmcnt(5)
	v_lshlrev_b32_e32 v18, 16, v103
	v_rcp_f32_e32 v3, v3
	v_mul_f32_e32 v2, v2, v18
	v_mul_f32_e32 v2, v2, v36
	v_cvt_pk_bf16_f32 v178, v20, v2
	v_add_f32_e32 v2, v53, v177
	v_mul_f32_e32 v2, 0xbfb8aa3b, v2
	v_mul_f32_e32 v184, v3, v18
	v_exp_f32_e32 v18, v2
	v_or_b32_e32 v2, s40, v140
	v_ashrrev_i32_e32 v3, 31, v2
	v_lshlrev_b64 v[112:113], 12, v[2:3]
	v_add_f32_e32 v2, 1.0, v18
	v_rcp_f32_e64 v2, -v2
	v_add_f32_e32 v21, v21, v173
	v_add_f32_e32 v3, v37, v175
	v_mul_f32_e32 v21, 0xbfb8aa3b, v21
	v_mul_f32_e32 v3, 0xbfb8aa3b, v3
	v_mul_f32_e32 v2, v176, v2
	v_exp_f32_e32 v21, v21
	v_exp_f32_e32 v36, v3
	v_bfe_u32 v3, v2, 16, 1
	v_add3_u32 v2, v2, v3, s61
	v_and_b32_e32 v37, 0xffff0000, v2
	v_exp_f32_e32 v18, v37
	v_add_f32_e32 v21, 1.0, v21
	v_rcp_f32_e64 v21, -v21
	v_add_f32_e32 v36, 1.0, v36
	v_fma_f32 v53, -v18, v18, 1.0
	v_max_f32_e32 v53, 0, v53
	v_mul_f32_e32 v21, v174, v21
	v_sqrt_f32_e32 v88, v53
	v_bfe_u32 v53, v21, 16, 1
	v_add_f32_e32 v5, v5, v172
	v_add3_u32 v21, v21, v53, s61
	v_rcp_f32_e32 v36, v36
	v_mul_f32_e32 v5, 0xbfb8aa3b, v5
	v_and_b32_e32 v21, 0xffff0000, v21
	v_exp_f32_e32 v5, v5
	v_exp_f32_e32 v53, v21
	s_waitcnt lgkmcnt(4)
; __device__ __forceinline__ unsigned f2bf(float f) { unsigned u = __builtin_bit_cast(unsigned, f); return (u + 0x7fffu + ((u >> 16) & 1u)) >> 16; }
; __device__ __forceinline__ unsigned pk2(float lo, float hi) { return cvtpk(lo, hi); }
; __device__ __forceinline__ float bflo(unsigned w) { return __uint_as_float(w << 16); }
; __device__ __forceinline__ float bf2f(bf16_t v) { return __uint_as_float((unsigned)v << 16); }
; __device__ __forceinline__ int crow(int r, int hi) { return (r & 3) + 8 * (r >> 2) + 4 * hi; }
; __device__ __forceinline__ float sigmoidf_(float x) { return __builtin_amdgcn_rcpf(1.f + __builtin_amdgcn_exp2f(-1.4426950408889634f * x)); }
; __device__ __forceinline__ void gates_phase(const GAS float* __restrict__ cw, const GAS float* __restrict__ cb, const GAS float* __restrict__ b_a, const GAS float* __restrict__ b_x, const GAS float* __restrict__ lam, LAS unsigned char* lds, const GAS bf16_t* __restrict__ P, const GAS bf16_t* __restr ...
;     ...
;             for (int i = 0; i < 16; ++i) { const int row = crow(i, hi); const float xv = bf2f(xs[row * 72 + ch]);
; #pragma unroll
;                 for (int d = 0; d < 2; ++d) { const float r = sigmoidf_(acc4[2 * d][i] + ba[d]), ig = sigmoidf_(acc4[2 * d + 1][i] + bx[d]);
;                     const float la2 = bflo(f2bf(-r * sp[d])), av = __builtin_amdgcn_exp2f(la2); avs[i][d] = av;
;                     const float uu = __builtin_amdgcn_sqrtf(fmaxf(1.f - av * av, 0.f)) * (ig * xv);
;                     wv[i][d] = pk2(la2, uu);
;                     __builtin_nontemporal_store(wv[i][d], LU + ((size_t)(m0 + row) * 2 + d) * 512 + gch); } }
	v_lshlrev_b32_e32 v20, 16, v104
	v_mul_f32_e32 v36, v36, v20
	v_mul_f32_e32 v36, v88, v36
	v_add_f32_e32 v5, 1.0, v5
	v_fma_f32 v88, -v53, v53, 1.0
	v_rcp_f32_e32 v5, v5
	v_max_f32_e32 v88, 0, v88
	v_sqrt_f32_e32 v88, v88
	v_lshl_add_u64 v[2:3], v[122:123], 0, v[112:113]
	v_mul_f32_e32 v5, v5, v20
	v_cvt_pk_bf16_f32 v185, v37, v36
	v_mul_f32_e32 v5, v5, v88
	v_cvt_pk_bf16_f32 v179, v21, v5
	v_add_f32_e32 v5, v54, v177
	v_mul_f32_e32 v5, 0xbfb8aa3b, v5
	v_exp_f32_e32 v5, v5
	global_store_dword v[2:3], v185, off nt
	global_store_dword v[2:3], v179, off offset:2048 nt
	v_or_b32_e32 v2, s40, v141
	v_add_f32_e32 v3, 1.0, v5
	v_rcp_f32_e64 v3, -v3
	v_add_f32_e32 v5, v38, v175
	v_mul_f32_e32 v5, 0xbfb8aa3b, v5
	v_exp_f32_e32 v5, v5
	v_mul_f32_e32 v3, v176, v3
	v_bfe_u32 v20, v3, 16, 1
	v_add3_u32 v3, v3, v20, s61
	v_and_b32_e32 v37, 0xffff0000, v3
	v_ashrrev_i32_e32 v3, 31, v2
	v_lshlrev_b64 v[110:111], 12, v[2:3]
	v_add_f32_e32 v3, v6, v172
	v_mul_f32_e32 v3, 0xbfb8aa3b, v3
	v_exp_f32_e32 v3, v3
	v_add_f32_e32 v5, 1.0, v5
	v_rcp_f32_e32 v5, v5
	v_exp_f32_e32 v207, v37
	v_add_f32_e32 v3, 1.0, v3
	v_rcp_f32_e32 v6, v3
	s_waitcnt lgkmcnt(3)
	v_lshlrev_b32_e32 v36, 16, v105
	v_mul_f32_e32 v2, v5, v36
	v_fma_f32 v20, -v207, v207, 1.0
	v_mul_f32_e32 v36, v6, v36
	v_add_f32_e32 v6, v55, v177
	v_mul_f32_e32 v6, 0xbfb8aa3b, v6
	v_exp_f32_e32 v6, v6
	v_max_f32_e32 v20, 0, v20
	v_sqrt_f32_e32 v38, v20
	v_add_f32_e32 v23, v23, v173
	v_add_f32_e32 v6, 1.0, v6
	v_rcp_f32_e64 v6, -v6
	v_mul_f32_e32 v2, v38, v2
	v_cvt_pk_bf16_f32 v208, v37, v2
	v_add_f32_e32 v2, v22, v173
	v_mul_f32_e32 v2, 0xbfb8aa3b, v2
	v_mul_f32_e32 v23, 0xbfb8aa3b, v23
	v_exp_f32_e32 v2, v2
	v_mul_f32_e32 v6, v176, v6
	v_exp_f32_e32 v23, v23
	v_bfe_u32 v37, v6, 16, 1
	v_or_b32_e32 v54, s40, v142
	v_add_f32_e32 v22, v39, v175
	v_add3_u32 v6, v6, v37, s61
	v_ashrrev_i32_e32 v55, 31, v54
	v_mul_f32_e32 v22, 0xbfb8aa3b, v22
	v_and_b32_e32 v6, 0xffff0000, v6
	v_add_f32_e32 v2, 1.0, v2
	v_lshlrev_b64 v[108:109], 12, v[54:55]
	v_exp_f32_e32 v22, v22
	v_exp_f32_e32 v55, v6
	v_add_f32_e32 v23, 1.0, v23
	v_rcp_f32_e64 v2, -v2
	v_rcp_f32_e64 v23, -v23
	v_add_f32_e32 v7, v7, v172
	v_add_f32_e32 v22, 1.0, v22
	v_fma_f32 v37, -v55, v55, 1.0
	v_mul_f32_e32 v7, 0xbfb8aa3b, v7
	v_mul_f32_e32 v2, v174, v2
	v_rcp_f32_e32 v22, v22
	v_max_f32_e32 v37, 0, v37
	v_exp_f32_e32 v38, v7
	v_mul_f32_e32 v7, v174, v23
	v_bfe_u32 v3, v2, 16, 1
	v_sqrt_f32_e32 v37, v37
	v_bfe_u32 v23, v7, 16, 1
	v_add3_u32 v2, v2, v3, s61
	v_add3_u32 v7, v7, v23, s61
	v_and_b32_e32 v5, 0xffff0000, v2
	s_waitcnt lgkmcnt(2)
	v_lshlrev_b32_e32 v2, 16, v106
	v_and_b32_e32 v23, 0xffff0000, v7
	v_mul_f32_e32 v22, v22, v2
	v_exp_f32_e32 v7, v23
	v_mul_f32_e32 v22, v37, v22
	v_cvt_pk_bf16_f32 v209, v6, v22
	v_add_f32_e32 v6, v56, v177
	v_mul_f32_e32 v6, 0xbfb8aa3b, v6
	v_add_f32_e32 v37, 1.0, v38
	v_fma_f32 v38, -v7, v7, 1.0
	v_exp_f32_e32 v6, v6
	v_rcp_f32_e32 v37, v37
	v_max_f32_e32 v38, 0, v38
	v_sqrt_f32_e32 v38, v38
	v_add_f32_e32 v6, 1.0, v6
	v_mul_f32_e32 v2, v37, v2
	v_rcp_f32_e64 v6, -v6
	v_mul_f32_e32 v2, v38, v2
	v_or_b32_e32 v22, s40, v143
	v_cvt_pk_bf16_f32 v38, v23, v2
	v_ashrrev_i32_e32 v23, 31, v22
	v_add_f32_e32 v24, v24, v173
	s_waitcnt lgkmcnt(1)
	v_lshlrev_b32_e32 v2, 16, v107
	v_lshlrev_b64 v[106:107], 12, v[22:23]
	v_add_f32_e32 v22, v40, v175
	v_mul_f32_e32 v24, 0xbfb8aa3b, v24
	v_mul_f32_e32 v22, 0xbfb8aa3b, v22
	v_mul_f32_e32 v6, v176, v6
	v_exp_f32_e32 v24, v24
	v_exp_f32_e32 v37, v22
	v_bfe_u32 v22, v6, 16, 1
	v_add3_u32 v6, v6, v22, s61
	v_and_b32_e32 v6, 0xffff0000, v6
	v_exp_f32_e32 v56, v6
	v_add_f32_e32 v24, 1.0, v24
	v_rcp_f32_e64 v24, -v24
	v_add_f32_e32 v37, 1.0, v37
	v_fma_f32 v39, -v56, v56, 1.0
	v_rcp_f32_e32 v37, v37
	v_max_f32_e32 v39, 0, v39
	v_mul_f32_e32 v24, v174, v24
	v_sqrt_f32_e32 v40, v39
	v_bfe_u32 v39, v24, 16, 1
	v_add_f32_e32 v8, v8, v172
	v_add3_u32 v24, v24, v39, s61
	v_mul_f32_e32 v8, 0xbfb8aa3b, v8
	v_and_b32_e32 v24, 0xffff0000, v24
	v_mul_f32_e32 v37, v37, v2
	v_exp_f32_e32 v8, v8
	v_exp_f32_e32 v39, v24
	v_mul_f32_e32 v37, v40, v37
	v_cvt_pk_bf16_f32 v210, v6, v37
	v_add_f32_e32 v6, v57, v177
	v_mul_f32_e32 v6, 0xbfb8aa3b, v6
	v_add_f32_e32 v8, 1.0, v8
	v_fma_f32 v40, -v39, v39, 1.0
	v_exp_f32_e32 v6, v6
	v_rcp_f32_e32 v8, v8
	v_max_f32_e32 v40, 0, v40
	v_sqrt_f32_e32 v40, v40
	v_add_f32_e32 v6, 1.0, v6
	v_add_f32_e32 v25, v25, v173
	v_mul_f32_e32 v2, v8, v2
	v_rcp_f32_e64 v6, -v6
	v_mul_f32_e32 v25, 0xbfb8aa3b, v25
	v_mul_f32_e32 v2, v40, v2
	v_exp_f32_e32 v25, v25
	v_lshl_add_u64 v[22:23], v[122:123], 0, v[106:107]
	v_cvt_pk_bf16_f32 v40, v24, v2
	global_store_dword v[22:23], v210, off nt
	global_store_dword v[22:23], v40, off offset:2048 nt
	v_or_b32_e32 v22, s40, v144
	v_ashrrev_i32_e32 v23, 31, v22
	v_mul_f32_e32 v6, v176, v6
	v_lshlrev_b64 v[104:105], 12, v[22:23]
	v_bfe_u32 v22, v6, 16, 1
	v_add_f32_e32 v25, 1.0, v25
	v_add_f32_e32 v8, v41, v175
	v_add3_u32 v6, v6, v22, s61
	v_rcp_f32_e64 v25, -v25
	v_mul_f32_e32 v8, 0xbfb8aa3b, v8
	v_and_b32_e32 v6, 0xffff0000, v6
	v_exp_f32_e32 v8, v8
	v_exp_f32_e32 v57, v6
	v_mul_f32_e32 v25, v174, v25
	v_bfe_u32 v37, v25, 16, 1
	v_add_f32_e32 v8, 1.0, v8
	v_fma_f32 v24, -v57, v57, 1.0
	v_add_f32_e32 v9, v9, v172
	v_add3_u32 v25, v25, v37, s61
	v_rcp_f32_e32 v8, v8
	v_max_f32_e32 v24, 0, v24
	v_mul_f32_e32 v9, 0xbfb8aa3b, v9
	v_and_b32_e32 v25, 0xffff0000, v25
	v_sqrt_f32_e32 v24, v24
	v_exp_f32_e32 v9, v9
	v_exp_f32_e32 v41, v25
	s_waitcnt lgkmcnt(0)
; __device__ __forceinline__ unsigned f2bf(float f) { unsigned u = __builtin_bit_cast(unsigned, f); return (u + 0x7fffu + ((u >> 16) & 1u)) >> 16; }
; __device__ __forceinline__ unsigned pk2(float lo, float hi) { return cvtpk(lo, hi); }
; __device__ __forceinline__ float bflo(unsigned w) { return __uint_as_float(w << 16); }
; __device__ __forceinline__ float bf2f(bf16_t v) { return __uint_as_float((unsigned)v << 16); }
; __device__ __forceinline__ int crow(int r, int hi) { return (r & 3) + 8 * (r >> 2) + 4 * hi; }
; __device__ __forceinline__ float sigmoidf_(float x) { return __builtin_amdgcn_rcpf(1.f + __builtin_amdgcn_exp2f(-1.4426950408889634f * x)); }
; __device__ __forceinline__ void gates_phase(const GAS float* __restrict__ cw, const GAS float* __restrict__ cb, const GAS float* __restrict__ b_a, const GAS float* __restrict__ b_x, const GAS float* __restrict__ lam, LAS unsigned char* lds, const GAS bf16_t* __restrict__ P, const GAS bf16_t* __restr ...
;     ...
;             for (int i = 0; i < 16; ++i) { const int row = crow(i, hi); const float xv = bf2f(xs[row * 72 + ch]);
; #pragma unroll
;                 for (int d = 0; d < 2; ++d) { const float r = sigmoidf_(acc4[2 * d][i] + ba[d]), ig = sigmoidf_(acc4[2 * d + 1][i] + bx[d]);
;                     const float la2 = bflo(f2bf(-r * sp[d])), av = __builtin_amdgcn_exp2f(la2); avs[i][d] = av;
;                     const float uu = __builtin_amdgcn_sqrtf(fmaxf(1.f - av * av, 0.f)) * (ig * xv);
;                     wv[i][d] = pk2(la2, uu);
;                     __builtin_nontemporal_store(wv[i][d], LU + ((size_t)(m0 + row) * 2 + d) * 512 + gch); } }
	v_lshlrev_b32_e32 v2, 16, v211
	v_mul_f32_e32 v8, v8, v2
	v_mul_f32_e32 v8, v24, v8
	v_add_f32_e32 v9, 1.0, v9
	v_fma_f32 v24, -v41, v41, 1.0
	v_rcp_f32_e32 v9, v9
	v_max_f32_e32 v24, 0, v24
	v_sqrt_f32_e32 v24, v24
	v_lshl_add_u64 v[22:23], v[122:123], 0, v[104:105]
	v_mul_f32_e32 v2, v9, v2
	v_cvt_pk_bf16_f32 v211, v6, v8
	v_mul_f32_e32 v2, v24, v2
	v_cvt_pk_bf16_f32 v54, v25, v2
	global_store_dword v[22:23], v211, off nt
	global_store_dword v[22:23], v54, off offset:2048 nt
	v_add_f32_e32 v6, v58, v177
	v_add_f32_e32 v22, v42, v175
	v_mul_f32_e32 v6, 0xbfb8aa3b, v6
	v_mul_f32_e32 v22, 0xbfb8aa3b, v22
	v_exp_f32_e32 v6, v6
	v_exp_f32_e32 v25, v22
	v_or_b32_e32 v8, s40, v145
	v_ashrrev_i32_e32 v9, 31, v8
	v_lshlrev_b64 v[102:103], 12, v[8:9]
	v_add_f32_e32 v6, 1.0, v6
	v_add_f32_e32 v8, 1.0, v25
	v_rcp_f32_e32 v9, v8
	v_rcp_f32_e64 v6, -v6
	v_add_f32_e32 v8, v26, v173
	v_mul_f32_e32 v8, 0xbfb8aa3b, v8
	v_exp_f32_e32 v8, v8
	v_mul_f32_e32 v6, v176, v6
	v_bfe_u32 v25, v6, 16, 1
	v_add3_u32 v25, v6, v25, s61
	v_add_f32_e32 v6, 1.0, v8
	v_rcp_f32_e64 v6, -v6
	v_add_f32_e32 v8, v10, v172
	v_mul_f32_e32 v8, 0xbfb8aa3b, v8
	v_exp_f32_e32 v8, v8
	v_mul_f32_e32 v6, v174, v6
	v_bfe_u32 v10, v6, 16, 1
	v_add3_u32 v6, v6, v10, s61
	v_and_b32_e32 v10, 0xffff0000, v6
	v_exp_f32_e32 v6, v10
	v_or_b32_e32 v50, s40, v137
	v_ashrrev_i32_e32 v51, 31, v50
	v_add_f32_e32 v8, 1.0, v8
	v_lshlrev_b64 v[120:121], 12, v[50:51]
	v_and_b32_e32 v215, 0xffff0000, v25
	v_rcp_f32_e32 v25, v8
	v_fma_f32 v8, -v6, v6, 1.0
	v_lshl_add_u64 v[82:83], v[122:123], 0, v[120:121]
	v_lshl_add_u64 v[50:51], v[122:123], 0, v[116:117]
	v_lshl_add_u64 v[20:21], v[122:123], 0, v[110:111]
	v_lshl_add_u64 v[88:89], v[122:123], 0, v[108:109]
	v_max_f32_e32 v8, 0, v8
	global_store_dword v[124:125], v182, off nt
	global_store_dword v[82:83], v183, off nt
	global_store_dword v[50:51], v178, off offset:2048 nt
	global_store_dword v[20:21], v208, off nt
	global_store_dword v[88:89], v209, off nt
	global_store_dword v[88:89], v38, off offset:2048 nt
	v_sqrt_f32_e32 v26, v8
	ds_read_u16 v2, v100 offset:2160
	ds_read_u16 v24, v100 offset:2304
	ds_read_u16 v37, v100 offset:2448
	ds_read_u16 v88, v100 offset:2592
	ds_read_u16 v89, v100 offset:3312
	ds_read_u16 v212, v100 offset:3456
	ds_read_u16 v213, v100 offset:3600
	ds_read_u16 v214, v100 offset:3744
	s_waitcnt lgkmcnt(7)
	v_lshlrev_b32_e32 v2, 16, v2
	v_mul_f32_e32 v216, v9, v2
	v_mul_f32_e32 v2, v25, v2
	v_mul_f32_e32 v2, v26, v2
	v_cvt_pk_bf16_f32 v42, v10, v2
	v_add_f32_e32 v2, v59, v177
	v_mul_f32_e32 v2, 0xbfb8aa3b, v2
	v_exp_f32_e32 v2, v2
	v_add_f32_e32 v10, v43, v175
	v_mul_f32_e32 v10, 0xbfb8aa3b, v10
	v_exp_f32_e32 v10, v10
	v_add_f32_e32 v2, 1.0, v2
	v_rcp_f32_e64 v2, -v2
	v_exp_f32_e32 v35, v85
	v_add_f32_e32 v10, 1.0, v10
	v_rcp_f32_e32 v26, v10
	v_mul_f32_e32 v2, v176, v2
	v_bfe_u32 v10, v2, 16, 1
	v_add3_u32 v2, v2, v10, s61
	v_and_b32_e32 v217, 0xffff0000, v2
	v_add_f32_e32 v2, v27, v173
	v_mul_f32_e32 v2, 0xbfb8aa3b, v2
	v_exp_f32_e32 v2, v2
	v_fma_f32 v27, -v35, v35, 1.0
	v_max_f32_e32 v27, 0, v27
	v_sqrt_f32_e32 v27, v27
	v_add_f32_e32 v2, 1.0, v2
	v_rcp_f32_e64 v2, -v2
	v_exp_f32_e32 v34, v86
	v_exp_f32_e32 v3, v5
	s_waitcnt lgkmcnt(6)
	v_lshlrev_b32_e32 v9, 16, v24
	v_mul_f32_e32 v2, v174, v2
	v_mul_f32_e32 v27, v84, v27
	v_mul_f32_e32 v218, v26, v9
	v_bfe_u32 v26, v2, 16, 1
	v_cvt_pk_bf16_f32 v58, v85, v27
	v_fma_f32 v27, -v34, v34, 1.0
	v_add_f32_e32 v11, v11, v172
	v_add3_u32 v2, v2, v26, s61
	v_max_f32_e32 v27, 0, v27
	v_fma_f32 v43, -v3, v3, 1.0
	v_mul_f32_e32 v11, 0xbfb8aa3b, v11
	v_and_b32_e32 v26, 0xffff0000, v2
	v_sqrt_f32_e32 v27, v27
	v_max_f32_e32 v43, 0, v43
	v_exp_f32_e32 v11, v11
	v_exp_f32_e32 v2, v26
	v_sqrt_f32_e32 v43, v43
	v_mul_f32_e32 v27, v87, v27
	v_add_f32_e32 v11, 1.0, v11
	global_store_dword v[124:125], v58, off offset:2048 nt
	v_cvt_pk_bf16_f32 v124, v86, v27
	v_mul_f32_e32 v27, v43, v36
	v_fma_f32 v36, -v2, v2, 1.0
	v_rcp_f32_e32 v11, v11
	v_max_f32_e32 v36, 0, v36
	v_sqrt_f32_e32 v36, v36
	v_cvt_pk_bf16_f32 v59, v5, v27
	v_mul_f32_e32 v5, v11, v9
	v_add_f32_e32 v9, v60, v177
	v_mul_f32_e32 v5, v36, v5
	v_cvt_pk_bf16_f32 v43, v26, v5
	v_mul_f32_e32 v9, 0xbfb8aa3b, v9
	v_add_f32_e32 v26, v28, v173
	v_exp_f32_e32 v9, v9
	v_mul_f32_e32 v26, 0xbfb8aa3b, v26
	v_exp_f32_e32 v26, v26
	v_add_f32_e32 v11, v44, v175
	v_add_f32_e32 v9, 1.0, v9
	v_rcp_f32_e64 v9, -v9
	v_add_f32_e32 v26, 1.0, v26
	v_rcp_f32_e64 v26, -v26
	v_add_f32_e32 v12, v12, v172
	v_mul_f32_e32 v9, v176, v9
	v_bfe_u32 v27, v9, 16, 1
	v_mul_f32_e32 v26, v174, v26
	v_add3_u32 v9, v9, v27, s61
	v_bfe_u32 v27, v26, 16, 1
	v_add3_u32 v26, v26, v27, s61
	v_mul_f32_e32 v11, 0xbfb8aa3b, v11
	v_mul_f32_e32 v12, 0xbfb8aa3b, v12
	v_and_b32_e32 v26, 0xffff0000, v26
	v_exp_f32_e32 v11, v11
	v_exp_f32_e32 v12, v12
	v_exp_f32_e32 v44, v26
	v_and_b32_e32 v125, 0xffff0000, v9
	v_add_f32_e32 v11, 1.0, v11
	v_add_f32_e32 v9, 1.0, v12
	v_fma_f32 v12, -v44, v44, 1.0
	v_rcp_f32_e32 v11, v11
	v_rcp_f32_e32 v9, v9
	v_max_f32_e32 v12, 0, v12
	v_sqrt_f32_e32 v27, v12
	s_waitcnt lgkmcnt(5)
; __device__ __forceinline__ unsigned f2bf(float f) { unsigned u = __builtin_bit_cast(unsigned, f); return (u + 0x7fffu + ((u >> 16) & 1u)) >> 16; }
; __device__ __forceinline__ unsigned pk2(float lo, float hi) { return cvtpk(lo, hi); }
; __device__ __forceinline__ float bflo(unsigned w) { return __uint_as_float(w << 16); }
; __device__ __forceinline__ float bf2f(bf16_t v) { return __uint_as_float((unsigned)v << 16); }
; __device__ __forceinline__ int crow(int r, int hi) { return (r & 3) + 8 * (r >> 2) + 4 * hi; }
; __device__ __forceinline__ float sigmoidf_(float x) { return __builtin_amdgcn_rcpf(1.f + __builtin_amdgcn_exp2f(-1.4426950408889634f * x)); }
; __device__ __forceinline__ void gates_phase(const GAS float* __restrict__ cw, const GAS float* __restrict__ cb, const GAS float* __restrict__ b_a, const GAS float* __restrict__ b_x, const GAS float* __restrict__ lam, LAS unsigned char* lds, const GAS bf16_t* __restrict__ P, const GAS bf16_t* __restr ...
;     ...
;             for (int i = 0; i < 16; ++i) { const int row = crow(i, hi); const float xv = bf2f(xs[row * 72 + ch]);
; #pragma unroll
;                 for (int d = 0; d < 2; ++d) { const float r = sigmoidf_(acc4[2 * d][i] + ba[d]), ig = sigmoidf_(acc4[2 * d + 1][i] + bx[d]);
;                     const float la2 = bflo(f2bf(-r * sp[d])), av = __builtin_amdgcn_exp2f(la2); avs[i][d] = av;
;                     const float uu = __builtin_amdgcn_sqrtf(fmaxf(1.f - av * av, 0.f)) * (ig * xv);
;                     wv[i][d] = pk2(la2, uu);
;                     __builtin_nontemporal_store(wv[i][d], LU + ((size_t)(m0 + row) * 2 + d) * 512 + gch); } }
	v_lshlrev_b32_e32 v5, 16, v37
	v_mul_f32_e32 v219, v11, v5
	v_mul_f32_e32 v5, v9, v5
	v_mul_f32_e32 v5, v27, v5
	v_cvt_pk_bf16_f32 v60, v26, v5
	v_or_b32_e32 v26, s40, v154
	v_ashrrev_i32_e32 v27, 31, v26
	v_add_f32_e32 v5, v61, v177
	v_mul_f32_e32 v5, 0xbfb8aa3b, v5
	v_lshlrev_b64 v[90:91], 12, v[26:27]
	v_add_f32_e32 v26, v29, v173
	v_exp_f32_e32 v5, v5
	v_mul_f32_e32 v26, 0xbfb8aa3b, v26
	v_exp_f32_e32 v26, v26
	v_add_f32_e32 v13, v13, v172
	v_add_f32_e32 v5, 1.0, v5
	v_rcp_f32_e64 v5, -v5
	v_add_f32_e32 v26, 1.0, v26
	v_rcp_f32_e64 v26, -v26
	v_add_f32_e32 v11, v45, v175
	v_mul_f32_e32 v5, v176, v5
	v_bfe_u32 v27, v5, 16, 1
	v_mul_f32_e32 v26, v174, v26
	v_add3_u32 v5, v5, v27, s61
	v_bfe_u32 v27, v26, 16, 1
	v_mul_f32_e32 v13, 0xbfb8aa3b, v13
	v_add3_u32 v26, v26, v27, s61
	v_mul_f32_e32 v11, 0xbfb8aa3b, v11
	v_exp_f32_e32 v13, v13
	v_and_b32_e32 v26, 0xffff0000, v26
	v_exp_f32_e32 v11, v11
	v_exp_f32_e32 v45, v26
	v_and_b32_e32 v220, 0xffff0000, v5
	v_add_f32_e32 v5, 1.0, v13
	v_add_f32_e32 v11, 1.0, v11
	v_rcp_f32_e32 v13, v5
	v_fma_f32 v5, -v45, v45, 1.0
	v_rcp_f32_e32 v11, v11
	v_max_f32_e32 v5, 0, v5
	v_sqrt_f32_e32 v27, v5
	s_waitcnt lgkmcnt(4)
	v_lshlrev_b32_e32 v9, 16, v88
	v_mul_f32_e32 v221, v11, v9
	v_mul_f32_e32 v9, v13, v9
	v_mul_f32_e32 v9, v27, v9
	v_cvt_pk_bf16_f32 v61, v26, v9
	v_add_f32_e32 v9, v62, v177
	v_mul_f32_e32 v9, 0xbfb8aa3b, v9
	v_add_f32_e32 v28, v30, v173
	v_exp_f32_e32 v9, v9
	v_mul_f32_e32 v28, 0xbfb8aa3b, v28
	v_exp_f32_e32 v28, v28
	v_add_f32_e32 v14, v14, v172
	v_add_f32_e32 v9, 1.0, v9
	v_rcp_f32_e64 v9, -v9
	v_add_f32_e32 v28, 1.0, v28
	v_rcp_f32_e64 v28, -v28
	v_add_f32_e32 v13, v46, v175
	v_mul_f32_e32 v9, v176, v9
	v_bfe_u32 v29, v9, 16, 1
	v_mul_f32_e32 v28, v174, v28
	v_add3_u32 v9, v9, v29, s61
	v_bfe_u32 v29, v28, 16, 1
	v_mul_f32_e32 v14, 0xbfb8aa3b, v14
	v_add3_u32 v28, v28, v29, s61
	v_mul_f32_e32 v13, 0xbfb8aa3b, v13
	v_exp_f32_e32 v14, v14
	v_and_b32_e32 v28, 0xffff0000, v28
	v_exp_f32_e32 v13, v13
	v_exp_f32_e32 v30, v28
	v_and_b32_e32 v222, 0xffff0000, v9
	v_add_f32_e32 v9, 1.0, v14
	v_add_f32_e32 v13, 1.0, v13
	v_rcp_f32_e32 v14, v9
	v_fma_f32 v9, -v30, v30, 1.0
	v_rcp_f32_e32 v13, v13
	v_max_f32_e32 v9, 0, v9
	v_sqrt_f32_e32 v29, v9
	s_waitcnt lgkmcnt(3)
	v_lshlrev_b32_e32 v11, 16, v89
	v_mul_f32_e32 v223, v13, v11
	v_mul_f32_e32 v11, v14, v11
	v_mul_f32_e32 v11, v29, v11
	v_cvt_pk_bf16_f32 v46, v28, v11
	v_add_f32_e32 v11, v63, v177
	v_mul_f32_e32 v11, 0xbfb8aa3b, v11
	v_add_f32_e32 v31, v31, v173
	v_exp_f32_e32 v11, v11
	v_mul_f32_e32 v31, 0xbfb8aa3b, v31
	v_exp_f32_e32 v31, v31
	v_add_f32_e32 v14, v47, v175
	v_add_f32_e32 v11, 1.0, v11
	v_rcp_f32_e64 v11, -v11
	v_add_f32_e32 v31, 1.0, v31
	v_rcp_f32_e64 v31, -v31
	v_add_f32_e32 v15, v15, v172
	v_mul_f32_e32 v11, v176, v11
	v_bfe_u32 v47, v11, 16, 1
	v_mul_f32_e32 v31, v174, v31
	v_add3_u32 v11, v11, v47, s61
	v_bfe_u32 v47, v31, 16, 1
	v_mul_f32_e32 v15, 0xbfb8aa3b, v15
	v_add3_u32 v31, v31, v47, s61
	v_mul_f32_e32 v14, 0xbfb8aa3b, v14
	v_exp_f32_e32 v15, v15
	v_and_b32_e32 v47, 0xffff0000, v31
	v_exp_f32_e32 v14, v14
	v_exp_f32_e32 v31, v47
	v_add_f32_e32 v62, v64, v177
	v_add_f32_e32 v63, v65, v177
	v_and_b32_e32 v177, 0xffff0000, v11
	v_add_f32_e32 v11, 1.0, v15
	v_add_f32_e32 v14, 1.0, v14
	v_rcp_f32_e32 v15, v11
	v_fma_f32 v11, -v31, v31, 1.0
	v_rcp_f32_e32 v14, v14
	v_max_f32_e32 v11, 0, v11
	v_sqrt_f32_e32 v64, v11
	s_waitcnt lgkmcnt(2)
	v_lshlrev_b32_e32 v13, 16, v212
	v_mul_f32_e32 v212, v14, v13
	v_mul_f32_e32 v13, v15, v13
	v_mul_f32_e32 v13, v64, v13
	v_cvt_pk_bf16_f32 v47, v47, v13
	v_mul_f32_e32 v13, 0xbfb8aa3b, v62
	v_add_f32_e32 v32, v32, v173
	v_exp_f32_e32 v13, v13
	v_mul_f32_e32 v32, 0xbfb8aa3b, v32
	v_exp_f32_e32 v32, v32
	v_add_f32_e32 v14, v48, v175
	v_add_f32_e32 v13, 1.0, v13
	v_rcp_f32_e64 v13, -v13
	v_add_f32_e32 v32, 1.0, v32
	v_rcp_f32_e64 v32, -v32
	v_mul_f32_e32 v14, 0xbfb8aa3b, v14
	v_exp_f32_e32 v14, v14
	v_mul_f32_e32 v13, v176, v13
	v_bfe_u32 v48, v13, 16, 1
	v_mul_f32_e32 v32, v174, v32
	v_add3_u32 v13, v13, v48, s61
	v_add_f32_e32 v16, v16, v172
	v_bfe_u32 v48, v32, 16, 1
	v_add_f32_e32 v14, 1.0, v14
	v_mul_f32_e32 v16, 0xbfb8aa3b, v16
	v_add3_u32 v32, v32, v48, s61
	v_rcp_f32_e32 v14, v14
	v_exp_f32_e32 v16, v16
	v_and_b32_e32 v48, 0xffff0000, v32
	v_exp_f32_e32 v32, v48
	s_waitcnt lgkmcnt(1)
	v_lshlrev_b32_e32 v15, 16, v213
	v_mul_f32_e32 v213, v14, v15
	v_add_f32_e32 v14, 1.0, v16
	v_rcp_f32_e32 v14, v14
	v_fma_f32 v16, -v32, v32, 1.0
	v_max_f32_e32 v16, 0, v16
	v_sqrt_f32_e32 v16, v16
	v_mul_f32_e32 v62, v14, v15
	v_or_b32_e32 v14, s40, v157
	v_mul_f32_e32 v63, 0xbfb8aa3b, v63
	v_add_f32_e32 v33, v33, v173
	v_ashrrev_i32_e32 v15, 31, v14
	v_exp_f32_e32 v63, v63
	v_mul_f32_e32 v33, 0xbfb8aa3b, v33
	v_lshlrev_b64 v[84:85], 12, v[14:15]
	v_mul_f32_e32 v14, v16, v62
	v_exp_f32_e32 v33, v33
	v_cvt_pk_bf16_f32 v48, v48, v14
	v_or_b32_e32 v14, s40, v158
	v_ashrrev_i32_e32 v15, 31, v14
	global_store_dword v[82:83], v124, off offset:2048 nt
	v_add_f32_e32 v49, v49, v175
	v_lshlrev_b64 v[82:83], 12, v[14:15]
	v_add_f32_e32 v14, 1.0, v63
	v_mul_f32_e32 v49, 0xbfb8aa3b, v49
	v_rcp_f32_e64 v14, -v14
	v_add_f32_e32 v33, 1.0, v33
	v_exp_f32_e32 v49, v49
	v_rcp_f32_e64 v33, -v33
	v_mul_f32_e32 v14, v176, v14
	v_add_f32_e32 v17, v17, v172
	v_add_f32_e32 v15, 1.0, v49
	v_bfe_u32 v49, v14, 16, 1
	v_mul_f32_e32 v33, v174, v33
	v_add3_u32 v14, v14, v49, s61
	v_bfe_u32 v49, v33, 16, 1
	v_add3_u32 v33, v33, v49, s61
	v_mul_f32_e32 v17, 0xbfb8aa3b, v17
	v_and_b32_e32 v49, 0xffff0000, v33
	v_exp_f32_e32 v17, v17
	v_exp_f32_e32 v33, v49
	v_and_b32_e32 v63, 0xffff0000, v14
	s_waitcnt lgkmcnt(0)
; __device__ __forceinline__ float bfhi(unsigned w) { return __uint_as_float(w & 0xffff0000u); }
; __device__ __forceinline__ void gates_phase(const GAS float* __restrict__ cw, const GAS float* __restrict__ cb, const GAS float* __restrict__ b_a, const GAS float* __restrict__ b_x, const GAS float* __restrict__ lam, LAS unsigned char* lds, const GAS bf16_t* __restrict__ P, const GAS bf16_t* __restr ...
;     ...
;                     __builtin_nontemporal_store(wv[i][d], LU + ((size_t)(m0 + row) * 2 + d) * 512 + gch); } }
; #pragma unroll
;             for (int d = 0; d < 2; ++d) {
;                 float Ar[4], Ur[4];
; #pragma unroll
;                 for (int g = 0; g < 4; ++g) { float A = 1.f, U = 0.f;
; #pragma unroll
;                     for (int jj = 0; jj < 4; ++jj) { const int j = d ? 3 - jj : jj; const unsigned w = wv[4 * g + j][d]; const float av = avs[4 * g + j][d]; A *= av; U = av * U + bfhi(w); }
;                     Ar[g] = A; Ur[g] = U; }
;                 float A = 1.f, U = 0.f;
; #pragma unroll
;                 for (int gg = 0; gg < 4; ++gg) { const int g = d ? 3 - gg : gg;
;                     const float Ao = __shfl_xor(Ar[g], 32), Uo = __shfl_xor(Ur[g], 32);
;                     if (d == 0) { U = Ar[g] * U + Ur[g]; A *= Ar[g]; U = Ao * U + Uo; A *= Ao; }
;                     else        { U = Ao * U + Uo; A *= Ao; U = Ar[g] * U + Ur[g]; A *= Ar[g]; } }
;                 if (hi == 0) wagg[(wave * 2 + d) * 64 + ch] = (f32x2){A, U};
	v_lshlrev_b32_e32 v62, 16, v214
	v_add_f32_e32 v14, 1.0, v17
	v_fma_f32 v17, -v33, v33, 1.0
	v_rcp_f32_e32 v14, v14
	v_max_f32_e32 v17, 0, v17
	v_sqrt_f32_e32 v17, v17
	v_exp_f32_e32 v4, v19
	v_mul_f32_e32 v14, v14, v62
	v_exp_f32_e32 v8, v215
	v_mul_f32_e32 v14, v17, v14
	v_cvt_pk_bf16_f32 v49, v49, v14
	v_and_b32_e32 v14, 0xffff0000, v182
	v_fmac_f32_e32 v14, 0, v180
	v_and_b32_e32 v17, 0xffff0000, v183
	v_fmac_f32_e32 v17, v181, v14
	v_and_b32_e32 v14, 0xffff0000, v208
	v_fmac_f32_e32 v14, 0, v207
	v_mul_f32_e32 v172, v207, v55
	v_and_b32_e32 v175, 0xffff0000, v209
	v_fmac_f32_e32 v175, v55, v14
	v_mul_f32_e32 v14, v56, v172
	v_and_b32_e32 v172, 0xffff0000, v210
	v_fmac_f32_e32 v172, v56, v175
	v_fma_f32 v56, -v4, v4, 1.0
	v_and_b32_e32 v55, 0xffff0000, v211
	v_max_f32_e32 v56, 0, v56
	v_mul_f32_e32 v14, v57, v14
	v_fmac_f32_e32 v55, v57, v172
	v_sqrt_f32_e32 v56, v56
	v_fma_f32 v57, -v8, v8, 1.0
	v_max_f32_e32 v57, 0, v57
	v_sqrt_f32_e32 v57, v57
	v_exp_f32_e32 v10, v217
	v_mul_f32_e32 v56, v184, v56
	v_cvt_pk_bf16_f32 v19, v19, v56
	global_store_dword v[50:51], v19, off nt
	v_mul_f32_e32 v50, v57, v216
	v_lshl_add_u64 v[22:23], v[122:123], 0, v[102:103]
	v_cvt_pk_bf16_f32 v50, v215, v50
	global_store_dword v[22:23], v42, off offset:2048 nt
	global_store_dword v[22:23], v50, off nt
	v_fma_f32 v22, -v10, v10, 1.0
	v_exp_f32_e32 v12, v125
	v_max_f32_e32 v22, 0, v22
	v_sqrt_f32_e32 v22, v22
	v_or_b32_e32 v24, s40, v151
	v_exp_f32_e32 v5, v220
	v_ashrrev_i32_e32 v25, 31, v24
	v_fma_f32 v23, -v12, v12, 1.0
	v_lshlrev_b64 v[100:101], 12, v[24:25]
	v_max_f32_e32 v23, 0, v23
	v_mul_f32_e32 v22, v22, v218
	v_lshl_add_u64 v[24:25], v[122:123], 0, v[100:101]
	v_sqrt_f32_e32 v23, v23
	v_cvt_pk_bf16_f32 v22, v217, v22
	global_store_dword v[24:25], v43, off offset:2048 nt
	global_store_dword v[24:25], v22, off nt
	v_fma_f32 v24, -v5, v5, 1.0
	global_store_dword v[20:21], v59, off offset:2048 nt
	v_or_b32_e32 v20, s40, v153
	v_exp_f32_e32 v9, v222
	v_max_f32_e32 v24, 0, v24
	v_ashrrev_i32_e32 v21, 31, v20
	v_exp_f32_e32 v11, v177
	v_sqrt_f32_e32 v24, v24
	v_lshlrev_b64 v[92:93], 12, v[20:21]
	v_mul_f32_e32 v23, v23, v219
	v_lshl_add_u64 v[20:21], v[122:123], 0, v[92:93]
	v_cvt_pk_bf16_f32 v23, v125, v23
	global_store_dword v[20:21], v60, off offset:2048 nt
	v_exp_f32_e32 v173, v63
	global_store_dword v[20:21], v23, off nt
	v_fma_f32 v21, -v9, v9, 1.0
	v_mul_f32_e32 v20, v24, v221
	v_max_f32_e32 v21, 0, v21
	v_fma_f32 v24, -v11, v11, 1.0
	v_and_b32_e32 v16, 0xffff0000, v13
	v_sqrt_f32_e32 v21, v21
	v_max_f32_e32 v24, 0, v24
	v_lshl_add_u64 v[36:37], v[122:123], 0, v[90:91]
	v_exp_f32_e32 v13, v16
	v_cvt_pk_bf16_f32 v20, v220, v20
	v_sqrt_f32_e32 v24, v24
	global_store_dword v[36:37], v61, off offset:2048 nt
	global_store_dword v[36:37], v20, off nt
	v_fma_f32 v36, -v173, v173, 1.0
	v_rcp_f32_e32 v15, v15
	v_max_f32_e32 v36, 0, v36
	v_mul_f32_e32 v21, v21, v223
	v_sqrt_f32_e32 v36, v36
	v_cvt_pk_bf16_f32 v25, v222, v21
	v_mul_f32_e32 v21, v24, v212
	v_fma_f32 v24, -v13, v13, 1.0
	v_max_f32_e32 v24, 0, v24
	v_mul_f32_e32 v15, v15, v62
	v_sqrt_f32_e32 v24, v24
	v_mul_f32_e32 v15, v36, v15
	v_cvt_pk_bf16_f32 v36, v63, v15
	v_and_b32_e32 v15, 0xffff0000, v19
	v_and_b32_e32 v62, 0xffff0000, v185
	v_fmac_f32_e32 v15, v4, v17
	v_cvt_pk_bf16_f32 v37, v177, v21
	v_mul_f32_e32 v21, v24, v213
	v_fmac_f32_e32 v62, v18, v15
	v_and_b32_e32 v15, 0xffff0000, v50
	v_cvt_pk_bf16_f32 v24, v16, v21
	v_fmac_f32_e32 v15, 0, v8
	v_and_b32_e32 v16, 0xffff0000, v22
	v_fmac_f32_e32 v16, v10, v15
	v_and_b32_e32 v175, 0xffff0000, v23
	v_mul_f32_e32 v174, v180, v181
	v_fmac_f32_e32 v175, v12, v16
	v_pk_mul_f32 v[16:17], v[4:5], v[174:175]
	v_and_b32_e32 v19, 0xffff0000, v20
	v_and_b32_e32 v15, 0xffff0000, v25
	v_mov_b32_e32 v172, v5
	v_pk_mul_f32 v[16:17], v[18:19], v[16:17]
	v_pk_fma_f32 v[18:19], v[4:5], v[174:175], v[18:19]
	v_fmac_f32_e32 v15, 0, v9
	v_pk_mul_f32 v[4:5], v[8:9], v[10:11]
	v_and_b32_e32 v8, 0xffff0000, v37
	v_fmac_f32_e32 v8, v11, v15
	v_and_b32_e32 v10, 0xffff0000, v24
	v_pk_mul_f32 v[4:5], v[12:13], v[4:5]
	v_fmac_f32_e32 v10, v13, v8
	v_and_b32_e32 v9, 0xffff0000, v36
	v_pk_mul_f32 v[4:5], v[172:173], v[4:5]
	v_fmac_f32_e32 v9, v173, v10
	ds_bpermute_b32 v20, v99, v16
	ds_bpermute_b32 v21, v99, v62
	ds_bpermute_b32 v12, v99, v14
	ds_bpermute_b32 v8, v99, v55
	ds_bpermute_b32 v15, v99, v4
	ds_bpermute_b32 v13, v99, v19
	ds_bpermute_b32 v10, v99, v5
	ds_bpermute_b32 v11, v99, v9
	v_or_b32_e32 v26, s40, v155
	v_or_b32_e32 v28, s40, v156
	v_ashrrev_i32_e32 v27, 31, v26
	v_ashrrev_i32_e32 v29, 31, v28
	v_lshlrev_b64 v[88:89], 12, v[26:27]
	v_lshlrev_b64 v[86:87], 12, v[28:29]
	v_lshl_add_u64 v[26:27], v[122:123], 0, v[88:89]
	v_lshl_add_u64 v[28:29], v[122:123], 0, v[86:87]
	v_lshl_add_u64 v[64:65], v[122:123], 0, v[84:85]
	v_lshl_add_u64 v[122:123], v[122:123], 0, v[82:83]
	global_store_dword v[26:27], v46, off offset:2048 nt
	global_store_dword v[28:29], v47, off offset:2048 nt
	global_store_dword v[64:65], v48, off offset:2048 nt
	global_store_dword v[122:123], v49, off offset:2048 nt
	global_store_dword v[26:27], v25, off nt
	global_store_dword v[28:29], v37, off nt
	global_store_dword v[64:65], v24, off nt
	global_store_dword v[122:123], v36, off nt
	s_and_saveexec_b64 s[10:11], s[6:7]
	s_cbranch_execz .LBB0_220
	v_fmac_f32_e32 v62, 0, v16
	s_waitcnt lgkmcnt(6)
	v_fmac_f32_e32 v21, v62, v20
	v_fmac_f32_e32 v55, v14, v21
	s_waitcnt lgkmcnt(4)
	v_fmac_f32_e32 v8, v55, v12
	v_mul_f32_e32 v21, v4, v8
	v_pk_mul_f32 v[16:17], v[16:17], v[20:21]
	v_pk_add_f32 v[18:19], v[18:19], v[20:21]
	s_waitcnt lgkmcnt(3)
	v_mov_b32_e32 v8, v15
	v_mov_b32_e32 v18, v16
	v_pk_mul_f32 v[16:17], v[14:15], v[16:17]
	s_waitcnt lgkmcnt(2)
	v_pk_mul_f32 v[16:17], v[16:17], v[12:13]
	v_pk_fma_f32 v[12:13], v[14:15], v[18:19], v[12:13]
	v_mov_b32_e32 v14, v15
	v_mov_b32_e32 v17, v13
	v_pk_mul_f32 v[12:13], v[4:5], v[16:17]
	v_pk_fma_f32 v[8:9], v[4:5], v[16:17], v[8:9]
	v_pk_mul_f32 v[12:13], v[12:13], v[14:15]
	s_waitcnt lgkmcnt(0)
	v_pk_mov_b32 v[4:5], v[4:5], v[10:11] op_sel:[1,0]
	v_mov_b32_e32 v8, v12
	v_pk_mul_f32 v[12:13], v[4:5], v[12:13]
	v_pk_fma_f32 v[4:5], v[4:5], v[8:9], v[10:11]
	v_pk_mul_f32 v[12:13], v[12:13], v[10:11]
	s_nop 0
	v_mov_b32_e32 v13, v5
	ds_write_b64 v159, v[12:13] offset:36864
